# combo (accsnake MFMA order, no GEMM setprio, P7 prio) + LDS-DMA issued with SGPR base + 32-bit VGPR offset instead of per-DMA 64-bit VALU address adds (56 sites)
# speedup vs baseline: 1.0229x; 1.0049x over previous
.LBB0_101:
	ds_read_b128 v[154:157], v151
	ds_read_b128 v[158:161], v151 offset:1024
	ds_read_b128 v[162:165], v151 offset:2048
	ds_read_b128 v[166:169], v151 offset:3072
	ds_read_b128 v[170:173], v152
	ds_read_b128 v[174:177], v152 offset:1024
	ds_read_b128 v[188:191], v152 offset:2048
	ds_read_b128 v[192:195], v152 offset:3072
	s_add_u32 s40, s36, s38
	s_addc_u32 s41, s37, s39
	s_add_u32 s44, s40, 0x100
	s_addc_u32 s45, s41, 0
	s_add_u32 s42, s66, s38
	s_addc_u32 s43, s67, s39
	s_add_u32 s40, s40, 0x180
	s_addc_u32 s41, s41, 0
	s_cmpk_eq_i32 s38, 0x1f00
	s_cselect_b32 s41, s65, s41
	s_cselect_b32 s40, s64, s40
	s_cselect_b32 s43, s35, s43
	s_cselect_b32 s42, s34, s42
	s_cselect_b32 s45, s23, s45
	s_cselect_b32 s44, s22, s44
	s_mov_b32 m0, s57
	v_lshl_add_u64 v[178:179], v[146:147], 0, s[38:39]
	ds_read_b128 v[196:199], v153
	ds_read_b128 v[200:203], v153 offset:1024
	ds_read_b128 v[204:207], v153 offset:2048
	ds_read_b128 v[208:211], v153 offset:3072
	ds_read_b128 v[214:217], v153 offset:4096
	ds_read_b128 v[218:221], v153 offset:5120
	ds_read_b128 v[222:225], v153 offset:6144
	ds_read_b128 v[226:229], v153 offset:7168
	global_load_lds_dwordx4 v[178:179], off
	v_lshl_add_u64 v[178:179], v[148:149], 0, s[38:39]
	s_add_i32 m0, s47, 0xe000
	s_nop 0
	global_load_lds_dwordx4 v[178:179], off
	s_waitcnt vmcnt(8)
	s_waitcnt lgkmcnt(0)
	s_barrier
	s_waitcnt lgkmcnt(0)
	v_mfma_f32_16x16x32_bf16 v[126:129], v[154:157], v[196:199], v[126:129]
	v_mfma_f32_16x16x32_bf16 v[126:129], v[158:161], v[200:203], v[126:129]
	v_mfma_f32_16x16x32_bf16 v[122:125], v[166:169], v[200:203], v[122:125]
	v_mfma_f32_16x16x32_bf16 v[122:125], v[162:165], v[196:199], v[122:125]
	v_mfma_f32_16x16x32_bf16 v[110:113], v[162:165], v[204:207], v[110:113]
	v_mfma_f32_16x16x32_bf16 v[110:113], v[166:169], v[208:211], v[110:113]
	v_mfma_f32_16x16x32_bf16 v[118:121], v[158:161], v[208:211], v[118:121]
	v_mfma_f32_16x16x32_bf16 v[118:121], v[154:157], v[204:207], v[118:121]
	v_mfma_f32_16x16x32_bf16 v[102:105], v[154:157], v[214:217], v[102:105]
	v_mfma_f32_16x16x32_bf16 v[102:105], v[158:161], v[218:221], v[102:105]
	v_mfma_f32_16x16x32_bf16 v[94:97], v[166:169], v[218:221], v[94:97]
	v_mfma_f32_16x16x32_bf16 v[94:97], v[162:165], v[214:217], v[94:97]
	v_mfma_f32_16x16x32_bf16 v[78:81], v[162:165], v[222:225], v[78:81]
	v_mfma_f32_16x16x32_bf16 v[78:81], v[166:169], v[226:229], v[78:81]
	v_mfma_f32_16x16x32_bf16 v[86:89], v[158:161], v[226:229], v[86:89]
	v_mfma_f32_16x16x32_bf16 v[86:89], v[154:157], v[222:225], v[86:89]
	v_mfma_f32_16x16x32_bf16 v[114:117], v[170:173], v[196:199], v[114:117]
	v_mfma_f32_16x16x32_bf16 v[114:117], v[174:177], v[200:203], v[114:117]
	v_mfma_f32_16x16x32_bf16 v[106:109], v[192:195], v[200:203], v[106:109]
	v_mfma_f32_16x16x32_bf16 v[106:109], v[188:191], v[196:199], v[106:109]
	v_mfma_f32_16x16x32_bf16 v[90:93], v[188:191], v[204:207], v[90:93]
	v_mfma_f32_16x16x32_bf16 v[90:93], v[192:195], v[208:211], v[90:93]
	v_mfma_f32_16x16x32_bf16 v[98:101], v[174:177], v[208:211], v[98:101]
	v_mfma_f32_16x16x32_bf16 v[98:101], v[170:173], v[204:207], v[98:101]
	v_mfma_f32_16x16x32_bf16 v[82:85], v[170:173], v[214:217], v[82:85]
	v_mfma_f32_16x16x32_bf16 v[82:85], v[174:177], v[218:221], v[82:85]
	v_mfma_f32_16x16x32_bf16 v[74:77], v[192:195], v[218:221], v[74:77]
	v_mfma_f32_16x16x32_bf16 v[74:77], v[188:191], v[214:217], v[74:77]
	v_mfma_f32_16x16x32_bf16 v[66:69], v[188:191], v[222:225], v[66:69]
	v_mfma_f32_16x16x32_bf16 v[66:69], v[192:195], v[226:229], v[66:69]
	v_mfma_f32_16x16x32_bf16 v[70:73], v[174:177], v[226:229], v[70:73]
	v_mfma_f32_16x16x32_bf16 v[70:73], v[170:173], v[222:225], v[70:73]
	s_barrier
	s_add_i32 s69, s54, s3
	v_lshl_add_u64 v[178:179], s[42:43], 0, v[136:137]
	s_mov_b32 m0, s69
	ds_read_b128 v[196:199], v153 offset:16384
	ds_read_b128 v[200:203], v153 offset:17408
	ds_read_b128 v[204:207], v153 offset:18432
	ds_read_b128 v[208:211], v153 offset:19456
	ds_read_b128 v[214:217], v153 offset:20480
	ds_read_b128 v[218:221], v153 offset:21504
	ds_read_b128 v[222:225], v153 offset:22528
	ds_read_b128 v[226:229], v153 offset:23552
	global_load_lds_dwordx4 v[178:179], off
	s_add_i32 m0, s69, 0x2000
	s_add_u32 s70, s42, 0x108000
	v_lshl_add_u64 v[230:231], s[42:43], 0, v[140:141]
	s_addc_u32 s71, s43, 0
	s_add_i32 s69, s55, s3
	global_load_lds_dwordx4 v[230:231], off
	s_mov_b32 m0, s69
	s_nop 0
	global_load_lds_dwordx4 v136, s[70:71]
	s_add_i32 m0, s69, 0x2000
	s_nop 0
	global_load_lds_dwordx4 v140, s[70:71]
	s_mov_b32 m0, s47
	s_nop 0
	global_load_lds_dwordx4 v134, s[44:45]
	s_mov_b32 m0, s48
	s_nop 0
	global_load_lds_dwordx4 v138, s[44:45]
	s_waitcnt vmcnt(8)
	s_waitcnt lgkmcnt(0)
	s_barrier
	s_waitcnt lgkmcnt(0)
	v_mfma_f32_16x16x32_bf16 v[62:65], v[154:157], v[196:199], v[62:65]
	v_mfma_f32_16x16x32_bf16 v[62:65], v[158:161], v[200:203], v[62:65]
	v_mfma_f32_16x16x32_bf16 v[58:61], v[166:169], v[200:203], v[58:61]
	v_mfma_f32_16x16x32_bf16 v[58:61], v[162:165], v[196:199], v[58:61]
	v_mfma_f32_16x16x32_bf16 v[46:49], v[162:165], v[204:207], v[46:49]
	v_mfma_f32_16x16x32_bf16 v[46:49], v[166:169], v[208:211], v[46:49]
	v_mfma_f32_16x16x32_bf16 v[54:57], v[158:161], v[208:211], v[54:57]
	v_mfma_f32_16x16x32_bf16 v[54:57], v[154:157], v[204:207], v[54:57]
	v_mfma_f32_16x16x32_bf16 v[38:41], v[154:157], v[214:217], v[38:41]
	v_mfma_f32_16x16x32_bf16 v[38:41], v[158:161], v[218:221], v[38:41]
	v_mfma_f32_16x16x32_bf16 v[30:33], v[166:169], v[218:221], v[30:33]
	v_mfma_f32_16x16x32_bf16 v[30:33], v[162:165], v[214:217], v[30:33]
	v_mfma_f32_16x16x32_bf16 v[14:17], v[162:165], v[222:225], v[14:17]
	v_mfma_f32_16x16x32_bf16 v[14:17], v[166:169], v[226:229], v[14:17]
	v_mfma_f32_16x16x32_bf16 v[22:25], v[158:161], v[226:229], v[22:25]
	v_mfma_f32_16x16x32_bf16 v[22:25], v[154:157], v[222:225], v[22:25]
	v_mfma_f32_16x16x32_bf16 v[50:53], v[170:173], v[196:199], v[50:53]
	v_mfma_f32_16x16x32_bf16 v[50:53], v[174:177], v[200:203], v[50:53]
	v_mfma_f32_16x16x32_bf16 v[42:45], v[192:195], v[200:203], v[42:45]
	v_mfma_f32_16x16x32_bf16 v[42:45], v[188:191], v[196:199], v[42:45]
	v_mfma_f32_16x16x32_bf16 v[26:29], v[188:191], v[204:207], v[26:29]
	v_mfma_f32_16x16x32_bf16 v[26:29], v[192:195], v[208:211], v[26:29]
	v_mfma_f32_16x16x32_bf16 v[34:37], v[174:177], v[208:211], v[34:37]
	v_mfma_f32_16x16x32_bf16 v[34:37], v[170:173], v[204:207], v[34:37]
	v_mfma_f32_16x16x32_bf16 v[18:21], v[170:173], v[214:217], v[18:21]
	v_mfma_f32_16x16x32_bf16 v[18:21], v[174:177], v[218:221], v[18:21]
	v_mfma_f32_16x16x32_bf16 v[10:13], v[192:195], v[218:221], v[10:13]
	v_mfma_f32_16x16x32_bf16 v[10:13], v[188:191], v[214:217], v[10:13]
	v_mfma_f32_16x16x32_bf16 v[2:5], v[188:191], v[222:225], v[2:5]
	v_mfma_f32_16x16x32_bf16 v[2:5], v[192:195], v[226:229], v[2:5]
	v_mfma_f32_16x16x32_bf16 v[6:9], v[174:177], v[226:229], v[6:9]
	v_mfma_f32_16x16x32_bf16 v[6:9], v[170:173], v[222:225], v[6:9]
	s_barrier
	s_add_i32 s69, 0, 0x18000
	s_add_i32 s70, 0, 0x1c000
	v_add_u32_e32 v166, s69, v133
	v_add_u32_e32 v187, s70, v133
	ds_read_b128 v[154:157], v166
	ds_read_b128 v[158:161], v166 offset:1024
	ds_read_b128 v[162:165], v166 offset:2048
	ds_read_b128 v[166:169], v166 offset:3072
	ds_read_b128 v[170:173], v187
	ds_read_b128 v[174:177], v187 offset:1024
	ds_read_b128 v[188:191], v187 offset:2048
	ds_read_b128 v[192:195], v187 offset:3072
	s_add_u32 s44, s44, 0x108000
	s_addc_u32 s45, s45, 0
	s_mov_b32 m0, s49
	ds_read_b128 v[196:199], v153 offset:32768
	ds_read_b128 v[200:203], v153 offset:33792
	ds_read_b128 v[204:207], v153 offset:34816
	ds_read_b128 v[208:211], v153 offset:35840
	ds_read_b128 v[214:217], v153 offset:36864
	ds_read_b128 v[218:221], v153 offset:37888
	ds_read_b128 v[222:225], v153 offset:38912
	ds_read_b128 v[226:229], v153 offset:39936
	global_load_lds_dwordx4 v134, s[44:45]
	v_lshl_add_u64 v[232:233], s[44:45], 0, v[138:139]
	s_mov_b32 m0, s50
	s_nop 0
	global_load_lds_dwordx4 v[232:233], off
	s_waitcnt vmcnt(8)
	s_waitcnt lgkmcnt(0)
	s_barrier
	s_waitcnt lgkmcnt(0)
	v_mfma_f32_16x16x32_bf16 v[126:129], v[154:157], v[196:199], v[126:129]
	v_mfma_f32_16x16x32_bf16 v[126:129], v[158:161], v[200:203], v[126:129]
	v_mfma_f32_16x16x32_bf16 v[122:125], v[166:169], v[200:203], v[122:125]
	v_mfma_f32_16x16x32_bf16 v[122:125], v[162:165], v[196:199], v[122:125]
	v_mfma_f32_16x16x32_bf16 v[110:113], v[162:165], v[204:207], v[110:113]
	v_mfma_f32_16x16x32_bf16 v[110:113], v[166:169], v[208:211], v[110:113]
	v_mfma_f32_16x16x32_bf16 v[118:121], v[158:161], v[208:211], v[118:121]
	v_mfma_f32_16x16x32_bf16 v[118:121], v[154:157], v[204:207], v[118:121]
	v_mfma_f32_16x16x32_bf16 v[102:105], v[154:157], v[214:217], v[102:105]
	v_mfma_f32_16x16x32_bf16 v[102:105], v[158:161], v[218:221], v[102:105]
	v_mfma_f32_16x16x32_bf16 v[94:97], v[166:169], v[218:221], v[94:97]
	v_mfma_f32_16x16x32_bf16 v[94:97], v[162:165], v[214:217], v[94:97]
	v_mfma_f32_16x16x32_bf16 v[78:81], v[162:165], v[222:225], v[78:81]
	v_mfma_f32_16x16x32_bf16 v[78:81], v[166:169], v[226:229], v[78:81]
	v_mfma_f32_16x16x32_bf16 v[86:89], v[158:161], v[226:229], v[86:89]
	v_mfma_f32_16x16x32_bf16 v[86:89], v[154:157], v[222:225], v[86:89]
	v_mfma_f32_16x16x32_bf16 v[114:117], v[170:173], v[196:199], v[114:117]
	v_mfma_f32_16x16x32_bf16 v[114:117], v[174:177], v[200:203], v[114:117]
	v_mfma_f32_16x16x32_bf16 v[106:109], v[192:195], v[200:203], v[106:109]
	v_mfma_f32_16x16x32_bf16 v[106:109], v[188:191], v[196:199], v[106:109]
	v_mfma_f32_16x16x32_bf16 v[90:93], v[188:191], v[204:207], v[90:93]
	v_mfma_f32_16x16x32_bf16 v[90:93], v[192:195], v[208:211], v[90:93]
	v_mfma_f32_16x16x32_bf16 v[98:101], v[174:177], v[208:211], v[98:101]
	v_mfma_f32_16x16x32_bf16 v[98:101], v[170:173], v[204:207], v[98:101]
	v_mfma_f32_16x16x32_bf16 v[82:85], v[170:173], v[214:217], v[82:85]
	v_mfma_f32_16x16x32_bf16 v[82:85], v[174:177], v[218:221], v[82:85]
	v_mfma_f32_16x16x32_bf16 v[74:77], v[192:195], v[218:221], v[74:77]
	v_mfma_f32_16x16x32_bf16 v[74:77], v[188:191], v[214:217], v[74:77]
	v_mfma_f32_16x16x32_bf16 v[66:69], v[188:191], v[222:225], v[66:69]
	v_mfma_f32_16x16x32_bf16 v[66:69], v[192:195], v[226:229], v[66:69]
	v_mfma_f32_16x16x32_bf16 v[70:73], v[174:177], v[226:229], v[70:73]
	v_mfma_f32_16x16x32_bf16 v[70:73], v[170:173], v[222:225], v[70:73]
	s_barrier
	s_add_i32 s44, s69, s3
	v_lshl_add_u64 v[178:179], v[178:179], 0, s[12:13]
	s_mov_b32 m0, s44
	ds_read_b128 v[196:199], v153 offset:49152
	ds_read_b128 v[200:203], v153 offset:50176
	ds_read_b128 v[204:207], v153 offset:51200
	ds_read_b128 v[208:211], v153 offset:52224
	ds_read_b128 v[214:217], v153 offset:53248
	ds_read_b128 v[218:221], v153 offset:54272
	ds_read_b128 v[222:225], v153 offset:55296
	ds_read_b128 v[226:229], v153 offset:56320
	global_load_lds_dwordx4 v[178:179], off
	s_add_i32 m0, s44, 0x2000
	s_add_u32 s42, s42, 0x108080
	v_lshl_add_u64 v[178:179], v[230:231], 0, s[12:13]
	s_addc_u32 s43, s43, 0
	s_add_i32 s44, s70, s3
	global_load_lds_dwordx4 v[178:179], off
	s_mov_b32 m0, s44
	s_nop 0
	global_load_lds_dwordx4 v136, s[42:43]
	s_add_i32 m0, s44, 0x2000
	s_nop 0
	global_load_lds_dwordx4 v140, s[42:43]
	s_mov_b32 m0, s52
	s_nop 0
	global_load_lds_dwordx4 v134, s[40:41]
	s_mov_b32 m0, s53
	s_nop 0
	global_load_lds_dwordx4 v138, s[40:41]
	s_waitcnt vmcnt(8)
	s_waitcnt lgkmcnt(0)
	s_barrier
	s_waitcnt lgkmcnt(0)
	v_mfma_f32_16x16x32_bf16 v[62:65], v[154:157], v[196:199], v[62:65]
	v_mfma_f32_16x16x32_bf16 v[62:65], v[158:161], v[200:203], v[62:65]
	v_mfma_f32_16x16x32_bf16 v[58:61], v[166:169], v[200:203], v[58:61]
	v_mfma_f32_16x16x32_bf16 v[58:61], v[162:165], v[196:199], v[58:61]
	v_mfma_f32_16x16x32_bf16 v[46:49], v[162:165], v[204:207], v[46:49]
	v_mfma_f32_16x16x32_bf16 v[46:49], v[166:169], v[208:211], v[46:49]
	v_mfma_f32_16x16x32_bf16 v[54:57], v[158:161], v[208:211], v[54:57]
	v_mfma_f32_16x16x32_bf16 v[54:57], v[154:157], v[204:207], v[54:57]
	v_mfma_f32_16x16x32_bf16 v[38:41], v[154:157], v[214:217], v[38:41]
	v_mfma_f32_16x16x32_bf16 v[38:41], v[158:161], v[218:221], v[38:41]
	v_mfma_f32_16x16x32_bf16 v[30:33], v[166:169], v[218:221], v[30:33]
	v_mfma_f32_16x16x32_bf16 v[30:33], v[162:165], v[214:217], v[30:33]
	v_mfma_f32_16x16x32_bf16 v[14:17], v[162:165], v[222:225], v[14:17]
	v_mfma_f32_16x16x32_bf16 v[14:17], v[166:169], v[226:229], v[14:17]
	v_mfma_f32_16x16x32_bf16 v[22:25], v[158:161], v[226:229], v[22:25]
	v_mfma_f32_16x16x32_bf16 v[22:25], v[154:157], v[222:225], v[22:25]
	v_mfma_f32_16x16x32_bf16 v[50:53], v[170:173], v[196:199], v[50:53]
	v_mfma_f32_16x16x32_bf16 v[50:53], v[174:177], v[200:203], v[50:53]
	v_mfma_f32_16x16x32_bf16 v[42:45], v[192:195], v[200:203], v[42:45]
	v_mfma_f32_16x16x32_bf16 v[42:45], v[188:191], v[196:199], v[42:45]
	v_mfma_f32_16x16x32_bf16 v[26:29], v[188:191], v[204:207], v[26:29]
	v_mfma_f32_16x16x32_bf16 v[26:29], v[192:195], v[208:211], v[26:29]
	v_mfma_f32_16x16x32_bf16 v[34:37], v[174:177], v[208:211], v[34:37]
	v_mfma_f32_16x16x32_bf16 v[34:37], v[170:173], v[204:207], v[34:37]
	v_mfma_f32_16x16x32_bf16 v[18:21], v[170:173], v[214:217], v[18:21]
	v_mfma_f32_16x16x32_bf16 v[18:21], v[174:177], v[218:221], v[18:21]
	v_mfma_f32_16x16x32_bf16 v[10:13], v[192:195], v[218:221], v[10:13]
	v_mfma_f32_16x16x32_bf16 v[10:13], v[188:191], v[214:217], v[10:13]
	v_mfma_f32_16x16x32_bf16 v[2:5], v[188:191], v[222:225], v[2:5]
	v_mfma_f32_16x16x32_bf16 v[2:5], v[192:195], v[226:229], v[2:5]
	v_mfma_f32_16x16x32_bf16 v[6:9], v[174:177], v[226:229], v[6:9]
	v_mfma_f32_16x16x32_bf16 v[6:9], v[170:173], v[222:225], v[6:9]
	s_barrier
	s_add_i32 s68, s68, 2
	s_add_u32 s38, s38, 0x100
	s_addc_u32 s39, s39, 0
	s_cmp_gt_u32 s68, 61
	s_cbranch_scc0 .LBB0_101
	s_and_b64 vcc, exec, s[20:21]
	s_cbranch_vccz .LBB0_104
	s_barrier

.LBB0_235:
	ds_read_b128 v[156:159], v150
	ds_read_b128 v[160:163], v150 offset:1024
	ds_read_b128 v[164:167], v150 offset:2048
	ds_read_b128 v[168:171], v150 offset:3072
	ds_read_b128 v[172:175], v151
	ds_read_b128 v[176:179], v151 offset:1024
	ds_read_b128 v[180:183], v151 offset:2048
	ds_read_b128 v[184:187], v151 offset:3072
	s_add_u32 s36, s4, s34
	s_addc_u32 s37, s5, s35
	s_add_u32 s40, s36, 0x100
	s_addc_u32 s41, s37, 0
	s_add_u32 s38, s62, s34
	s_addc_u32 s39, s63, s35
	s_add_u32 s36, s36, 0x180
	s_addc_u32 s37, s37, 0
	s_cmpk_eq_i32 s34, 0x1f00
	s_cselect_b32 s37, s61, s37
	s_cselect_b32 s36, s60, s36
	s_cselect_b32 s39, s31, s39
	s_cselect_b32 s38, s30, s38
	s_cselect_b32 s41, s23, s41
	s_cselect_b32 s40, s22, s40
	s_mov_b32 m0, s46
	v_lshl_add_u64 v[222:223], v[146:147], 0, s[34:35]
	ds_read_b128 v[188:191], v152
	ds_read_b128 v[192:195], v152 offset:1024
	ds_read_b128 v[196:199], v152 offset:2048
	ds_read_b128 v[200:203], v152 offset:3072
	ds_read_b128 v[204:207], v152 offset:4096
	ds_read_b128 v[208:211], v152 offset:5120
	ds_read_b128 v[214:217], v152 offset:6144
	ds_read_b128 v[218:221], v152 offset:7168
	global_load_lds_dwordx4 v[222:223], off
	v_lshl_add_u64 v[222:223], v[148:149], 0, s[34:35]
	s_mov_b32 m0, s47
	s_nop 0
	global_load_lds_dwordx4 v[222:223], off
	s_waitcnt vmcnt(8)
	s_waitcnt lgkmcnt(0)
	s_barrier
	s_waitcnt lgkmcnt(0)
	v_mfma_f32_16x16x32_bf16 v[126:129], v[156:159], v[188:191], v[126:129]
	v_mfma_f32_16x16x32_bf16 v[126:129], v[160:163], v[192:195], v[126:129]
	v_mfma_f32_16x16x32_bf16 v[122:125], v[168:171], v[192:195], v[122:125]
	v_mfma_f32_16x16x32_bf16 v[122:125], v[164:167], v[188:191], v[122:125]
	v_mfma_f32_16x16x32_bf16 v[106:109], v[164:167], v[196:199], v[106:109]
	v_mfma_f32_16x16x32_bf16 v[106:109], v[168:171], v[200:203], v[106:109]
	v_mfma_f32_16x16x32_bf16 v[110:113], v[160:163], v[200:203], v[110:113]
	v_mfma_f32_16x16x32_bf16 v[110:113], v[156:159], v[196:199], v[110:113]
	v_mfma_f32_16x16x32_bf16 v[94:97], v[156:159], v[204:207], v[94:97]
	v_mfma_f32_16x16x32_bf16 v[94:97], v[160:163], v[208:211], v[94:97]
	v_mfma_f32_16x16x32_bf16 v[90:93], v[168:171], v[208:211], v[90:93]
	v_mfma_f32_16x16x32_bf16 v[90:93], v[164:167], v[204:207], v[90:93]
	v_mfma_f32_16x16x32_bf16 v[74:77], v[164:167], v[214:217], v[74:77]
	v_mfma_f32_16x16x32_bf16 v[74:77], v[168:171], v[218:221], v[74:77]
	v_mfma_f32_16x16x32_bf16 v[78:81], v[160:163], v[218:221], v[78:81]
	v_mfma_f32_16x16x32_bf16 v[78:81], v[156:159], v[214:217], v[78:81]
	v_mfma_f32_16x16x32_bf16 v[118:121], v[172:175], v[188:191], v[118:121]
	v_mfma_f32_16x16x32_bf16 v[118:121], v[176:179], v[192:195], v[118:121]
	v_mfma_f32_16x16x32_bf16 v[114:117], v[184:187], v[192:195], v[114:117]
	v_mfma_f32_16x16x32_bf16 v[114:117], v[180:183], v[188:191], v[114:117]
	v_mfma_f32_16x16x32_bf16 v[98:101], v[180:183], v[196:199], v[98:101]
	v_mfma_f32_16x16x32_bf16 v[98:101], v[184:187], v[200:203], v[98:101]
	v_mfma_f32_16x16x32_bf16 v[102:105], v[176:179], v[200:203], v[102:105]
	v_mfma_f32_16x16x32_bf16 v[102:105], v[172:175], v[196:199], v[102:105]
	v_mfma_f32_16x16x32_bf16 v[86:89], v[172:175], v[204:207], v[86:89]
	v_mfma_f32_16x16x32_bf16 v[86:89], v[176:179], v[208:211], v[86:89]
	v_mfma_f32_16x16x32_bf16 v[82:85], v[184:187], v[208:211], v[82:85]
	v_mfma_f32_16x16x32_bf16 v[82:85], v[180:183], v[204:207], v[82:85]
	v_mfma_f32_16x16x32_bf16 v[66:69], v[180:183], v[214:217], v[66:69]
	v_mfma_f32_16x16x32_bf16 v[66:69], v[184:187], v[218:221], v[66:69]
	v_mfma_f32_16x16x32_bf16 v[70:73], v[176:179], v[218:221], v[70:73]
	v_mfma_f32_16x16x32_bf16 v[70:73], v[172:175], v[214:217], v[70:73]
	s_barrier
	s_mov_b32 m0, s48
	v_lshl_add_u64 v[222:223], s[38:39], 0, v[132:133]
	s_add_u32 s66, s38, 0x108000
	ds_read_b128 v[188:191], v152 offset:16384
	ds_read_b128 v[192:195], v152 offset:17408
	ds_read_b128 v[196:199], v152 offset:18432
	ds_read_b128 v[200:203], v152 offset:19456
	ds_read_b128 v[204:207], v152 offset:20480
	ds_read_b128 v[208:211], v152 offset:21504
	ds_read_b128 v[214:217], v152 offset:22528
	ds_read_b128 v[218:221], v152 offset:23552
	global_load_lds_dwordx4 v[222:223], off
	v_lshl_add_u64 v[224:225], s[38:39], 0, v[136:137]
	s_mov_b32 m0, s49
	s_addc_u32 s67, s39, 0
	global_load_lds_dwordx4 v[224:225], off
	s_mov_b32 m0, s50
	s_nop 0
	global_load_lds_dwordx4 v132, s[66:67]
	s_mov_b32 m0, s51
	s_nop 0
	global_load_lds_dwordx4 v136, s[66:67]
	s_mov_b32 m0, s3
	s_nop 0
	global_load_lds_dwordx4 v130, s[40:41]
	s_mov_b32 m0, s33
	s_nop 0
	global_load_lds_dwordx4 v134, s[40:41]
	s_waitcnt vmcnt(8)
	s_waitcnt lgkmcnt(0)
	s_barrier
	s_waitcnt lgkmcnt(0)
	v_mfma_f32_16x16x32_bf16 v[62:65], v[156:159], v[188:191], v[62:65]
	v_mfma_f32_16x16x32_bf16 v[62:65], v[160:163], v[192:195], v[62:65]
	v_mfma_f32_16x16x32_bf16 v[58:61], v[168:171], v[192:195], v[58:61]
	v_mfma_f32_16x16x32_bf16 v[58:61], v[164:167], v[188:191], v[58:61]
	v_mfma_f32_16x16x32_bf16 v[42:45], v[164:167], v[196:199], v[42:45]
	v_mfma_f32_16x16x32_bf16 v[42:45], v[168:171], v[200:203], v[42:45]
	v_mfma_f32_16x16x32_bf16 v[46:49], v[160:163], v[200:203], v[46:49]
	v_mfma_f32_16x16x32_bf16 v[46:49], v[156:159], v[196:199], v[46:49]
	v_mfma_f32_16x16x32_bf16 v[30:33], v[156:159], v[204:207], v[30:33]
	v_mfma_f32_16x16x32_bf16 v[30:33], v[160:163], v[208:211], v[30:33]
	v_mfma_f32_16x16x32_bf16 v[26:29], v[168:171], v[208:211], v[26:29]
	v_mfma_f32_16x16x32_bf16 v[26:29], v[164:167], v[204:207], v[26:29]
	v_mfma_f32_16x16x32_bf16 v[10:13], v[164:167], v[214:217], v[10:13]
	v_mfma_f32_16x16x32_bf16 v[10:13], v[168:171], v[218:221], v[10:13]
	v_mfma_f32_16x16x32_bf16 v[14:17], v[160:163], v[218:221], v[14:17]
	v_mfma_f32_16x16x32_bf16 v[14:17], v[156:159], v[214:217], v[14:17]
	v_mfma_f32_16x16x32_bf16 v[54:57], v[172:175], v[188:191], v[54:57]
	v_mfma_f32_16x16x32_bf16 v[54:57], v[176:179], v[192:195], v[54:57]
	v_mfma_f32_16x16x32_bf16 v[50:53], v[184:187], v[192:195], v[50:53]
	v_mfma_f32_16x16x32_bf16 v[50:53], v[180:183], v[188:191], v[50:53]
	v_mfma_f32_16x16x32_bf16 v[34:37], v[180:183], v[196:199], v[34:37]
	v_mfma_f32_16x16x32_bf16 v[34:37], v[184:187], v[200:203], v[34:37]
	v_mfma_f32_16x16x32_bf16 v[38:41], v[176:179], v[200:203], v[38:41]
	v_mfma_f32_16x16x32_bf16 v[38:41], v[172:175], v[196:199], v[38:41]
	v_mfma_f32_16x16x32_bf16 v[22:25], v[172:175], v[204:207], v[22:25]
	v_mfma_f32_16x16x32_bf16 v[22:25], v[176:179], v[208:211], v[22:25]
	v_mfma_f32_16x16x32_bf16 v[18:21], v[184:187], v[208:211], v[18:21]
	v_mfma_f32_16x16x32_bf16 v[18:21], v[180:183], v[204:207], v[18:21]
	v_mfma_f32_16x16x32_bf16 v[2:5], v[180:183], v[214:217], v[2:5]
	v_mfma_f32_16x16x32_bf16 v[2:5], v[184:187], v[218:221], v[2:5]
	v_mfma_f32_16x16x32_bf16 v[6:9], v[176:179], v[218:221], v[6:9]
	v_mfma_f32_16x16x32_bf16 v[6:9], v[172:175], v[214:217], v[6:9]
	s_barrier
	ds_read_b128 v[156:159], v153
	ds_read_b128 v[160:163], v153 offset:1024
	ds_read_b128 v[164:167], v153 offset:2048
	ds_read_b128 v[168:171], v153 offset:3072
	ds_read_b128 v[172:175], v154
	ds_read_b128 v[176:179], v154 offset:1024
	ds_read_b128 v[180:183], v154 offset:2048
	ds_read_b128 v[184:187], v154 offset:3072
	s_add_u32 s40, s40, 0x108000
	s_addc_u32 s41, s41, 0
	s_mov_b32 m0, s42
	ds_read_b128 v[188:191], v152 offset:32768
	ds_read_b128 v[192:195], v152 offset:33792
	ds_read_b128 v[196:199], v152 offset:34816
	ds_read_b128 v[200:203], v152 offset:35840
	ds_read_b128 v[204:207], v152 offset:36864
	ds_read_b128 v[208:211], v152 offset:37888
	ds_read_b128 v[214:217], v152 offset:38912
	ds_read_b128 v[218:221], v152 offset:39936
	global_load_lds_dwordx4 v130, s[40:41]
	v_lshl_add_u64 v[226:227], s[40:41], 0, v[134:135]
	s_mov_b32 m0, s43
	s_nop 0
	global_load_lds_dwordx4 v[226:227], off
	s_waitcnt vmcnt(8)
	s_waitcnt lgkmcnt(0)
	s_barrier
	s_waitcnt lgkmcnt(0)
	v_mfma_f32_16x16x32_bf16 v[126:129], v[156:159], v[188:191], v[126:129]
	v_mfma_f32_16x16x32_bf16 v[126:129], v[160:163], v[192:195], v[126:129]
	v_mfma_f32_16x16x32_bf16 v[122:125], v[168:171], v[192:195], v[122:125]
	v_mfma_f32_16x16x32_bf16 v[122:125], v[164:167], v[188:191], v[122:125]
	v_mfma_f32_16x16x32_bf16 v[106:109], v[164:167], v[196:199], v[106:109]
	v_mfma_f32_16x16x32_bf16 v[106:109], v[168:171], v[200:203], v[106:109]
	v_mfma_f32_16x16x32_bf16 v[110:113], v[160:163], v[200:203], v[110:113]
	v_mfma_f32_16x16x32_bf16 v[110:113], v[156:159], v[196:199], v[110:113]
	v_mfma_f32_16x16x32_bf16 v[94:97], v[156:159], v[204:207], v[94:97]
	v_mfma_f32_16x16x32_bf16 v[94:97], v[160:163], v[208:211], v[94:97]
	v_mfma_f32_16x16x32_bf16 v[90:93], v[168:171], v[208:211], v[90:93]
	v_mfma_f32_16x16x32_bf16 v[90:93], v[164:167], v[204:207], v[90:93]
	v_mfma_f32_16x16x32_bf16 v[74:77], v[164:167], v[214:217], v[74:77]
	v_mfma_f32_16x16x32_bf16 v[74:77], v[168:171], v[218:221], v[74:77]
	v_mfma_f32_16x16x32_bf16 v[78:81], v[160:163], v[218:221], v[78:81]
	v_mfma_f32_16x16x32_bf16 v[78:81], v[156:159], v[214:217], v[78:81]
	v_mfma_f32_16x16x32_bf16 v[118:121], v[172:175], v[188:191], v[118:121]
	v_mfma_f32_16x16x32_bf16 v[118:121], v[176:179], v[192:195], v[118:121]
	v_mfma_f32_16x16x32_bf16 v[114:117], v[184:187], v[192:195], v[114:117]
	v_mfma_f32_16x16x32_bf16 v[114:117], v[180:183], v[188:191], v[114:117]
	v_mfma_f32_16x16x32_bf16 v[98:101], v[180:183], v[196:199], v[98:101]
	v_mfma_f32_16x16x32_bf16 v[98:101], v[184:187], v[200:203], v[98:101]
	v_mfma_f32_16x16x32_bf16 v[102:105], v[176:179], v[200:203], v[102:105]
	v_mfma_f32_16x16x32_bf16 v[102:105], v[172:175], v[196:199], v[102:105]
	v_mfma_f32_16x16x32_bf16 v[86:89], v[172:175], v[204:207], v[86:89]
	v_mfma_f32_16x16x32_bf16 v[86:89], v[176:179], v[208:211], v[86:89]
	v_mfma_f32_16x16x32_bf16 v[82:85], v[184:187], v[208:211], v[82:85]
	v_mfma_f32_16x16x32_bf16 v[82:85], v[180:183], v[204:207], v[82:85]
	v_mfma_f32_16x16x32_bf16 v[66:69], v[180:183], v[214:217], v[66:69]
	v_mfma_f32_16x16x32_bf16 v[66:69], v[184:187], v[218:221], v[66:69]
	v_mfma_f32_16x16x32_bf16 v[70:73], v[176:179], v[218:221], v[70:73]
	v_mfma_f32_16x16x32_bf16 v[70:73], v[172:175], v[214:217], v[70:73]
	s_barrier
	s_mov_b32 m0, s53
	v_lshl_add_u64 v[222:223], v[222:223], 0, s[16:17]
	s_add_u32 s38, s38, 0x108080
	ds_read_b128 v[188:191], v152 offset:49152
	ds_read_b128 v[192:195], v152 offset:50176
	ds_read_b128 v[196:199], v152 offset:51200
	ds_read_b128 v[200:203], v152 offset:52224
	ds_read_b128 v[204:207], v152 offset:53248
	ds_read_b128 v[208:211], v152 offset:54272
	ds_read_b128 v[214:217], v152 offset:55296
	ds_read_b128 v[218:221], v152 offset:56320
	global_load_lds_dwordx4 v[222:223], off
	v_lshl_add_u64 v[222:223], v[224:225], 0, s[16:17]
	s_mov_b32 m0, s54
	s_addc_u32 s39, s39, 0
	s_add_i32 s40, s52, s2
	global_load_lds_dwordx4 v[222:223], off
	s_mov_b32 m0, s40
	s_nop 0
	global_load_lds_dwordx4 v132, s[38:39]
	s_add_i32 m0, s40, 0x2000
	s_nop 0
	global_load_lds_dwordx4 v136, s[38:39]
	s_mov_b32 m0, s44
	s_nop 0
	global_load_lds_dwordx4 v130, s[36:37]
	s_mov_b32 m0, s45
	s_nop 0
	global_load_lds_dwordx4 v134, s[36:37]
	s_waitcnt vmcnt(8)
	s_waitcnt lgkmcnt(0)
	s_barrier
	s_waitcnt lgkmcnt(0)
	v_mfma_f32_16x16x32_bf16 v[62:65], v[156:159], v[188:191], v[62:65]
	v_mfma_f32_16x16x32_bf16 v[62:65], v[160:163], v[192:195], v[62:65]
	v_mfma_f32_16x16x32_bf16 v[58:61], v[168:171], v[192:195], v[58:61]
	v_mfma_f32_16x16x32_bf16 v[58:61], v[164:167], v[188:191], v[58:61]
	v_mfma_f32_16x16x32_bf16 v[42:45], v[164:167], v[196:199], v[42:45]
	v_mfma_f32_16x16x32_bf16 v[42:45], v[168:171], v[200:203], v[42:45]
	v_mfma_f32_16x16x32_bf16 v[46:49], v[160:163], v[200:203], v[46:49]
	v_mfma_f32_16x16x32_bf16 v[46:49], v[156:159], v[196:199], v[46:49]
	v_mfma_f32_16x16x32_bf16 v[30:33], v[156:159], v[204:207], v[30:33]
	v_mfma_f32_16x16x32_bf16 v[30:33], v[160:163], v[208:211], v[30:33]
	v_mfma_f32_16x16x32_bf16 v[26:29], v[168:171], v[208:211], v[26:29]
	v_mfma_f32_16x16x32_bf16 v[26:29], v[164:167], v[204:207], v[26:29]
	v_mfma_f32_16x16x32_bf16 v[10:13], v[164:167], v[214:217], v[10:13]
	v_mfma_f32_16x16x32_bf16 v[10:13], v[168:171], v[218:221], v[10:13]
	v_mfma_f32_16x16x32_bf16 v[14:17], v[160:163], v[218:221], v[14:17]
	v_mfma_f32_16x16x32_bf16 v[14:17], v[156:159], v[214:217], v[14:17]
	v_mfma_f32_16x16x32_bf16 v[54:57], v[172:175], v[188:191], v[54:57]
	v_mfma_f32_16x16x32_bf16 v[54:57], v[176:179], v[192:195], v[54:57]
	v_mfma_f32_16x16x32_bf16 v[50:53], v[184:187], v[192:195], v[50:53]
	v_mfma_f32_16x16x32_bf16 v[50:53], v[180:183], v[188:191], v[50:53]
	v_mfma_f32_16x16x32_bf16 v[34:37], v[180:183], v[196:199], v[34:37]
	v_mfma_f32_16x16x32_bf16 v[34:37], v[184:187], v[200:203], v[34:37]
	v_mfma_f32_16x16x32_bf16 v[38:41], v[176:179], v[200:203], v[38:41]
	v_mfma_f32_16x16x32_bf16 v[38:41], v[172:175], v[196:199], v[38:41]
	v_mfma_f32_16x16x32_bf16 v[22:25], v[172:175], v[204:207], v[22:25]
	v_mfma_f32_16x16x32_bf16 v[22:25], v[176:179], v[208:211], v[22:25]
	v_mfma_f32_16x16x32_bf16 v[18:21], v[184:187], v[208:211], v[18:21]
	v_mfma_f32_16x16x32_bf16 v[18:21], v[180:183], v[204:207], v[18:21]
	v_mfma_f32_16x16x32_bf16 v[2:5], v[180:183], v[214:217], v[2:5]
	v_mfma_f32_16x16x32_bf16 v[2:5], v[184:187], v[218:221], v[2:5]
	v_mfma_f32_16x16x32_bf16 v[6:9], v[176:179], v[218:221], v[6:9]
	v_mfma_f32_16x16x32_bf16 v[6:9], v[172:175], v[214:217], v[6:9]
	s_barrier
	s_add_i32 s64, s64, 2
	s_add_u32 s34, s34, 0x100
	s_addc_u32 s35, s35, 0
	s_cmp_gt_u32 s64, 61
	s_cbranch_scc0 .LBB0_235
	s_and_b64 vcc, exec, s[20:21]
	s_cbranch_vccz .LBB0_238
	s_barrier

.LBB0_434:
	ds_read_b128 v[134:137], v204
	ds_read_b128 v[138:141], v204 offset:1024
	ds_read_b128 v[142:145], v204 offset:2048
	ds_read_b128 v[146:149], v204 offset:3072
	ds_read_b128 v[150:153], v205
	ds_read_b128 v[154:157], v205 offset:1024
	ds_read_b128 v[158:161], v205 offset:2048
	ds_read_b128 v[162:165], v205 offset:3072
	s_add_u32 s34, s22, s30
	s_addc_u32 s35, s23, s31
	s_add_u32 s38, s34, 0x100
	s_addc_u32 s39, s35, 0
	s_add_u32 s36, s60, s30
	s_addc_u32 s37, s61, s31
	s_add_u32 s34, s34, 0x180
	s_addc_u32 s35, s35, 0
	s_cmpk_eq_i32 s30, 0xb00
	s_cselect_b32 s35, s59, s35
	s_cselect_b32 s34, s58, s34
	s_cselect_b32 s37, s21, s37
	s_cselect_b32 s36, s20, s36
	s_cselect_b32 s39, s17, s39
	s_cselect_b32 s38, s16, s38
	v_lshl_add_u64 v[200:201], v[130:131], 0, s[30:31]
	s_add_i32 m0, s3, 0xc000
	ds_read_b128 v[166:169], v206
	ds_read_b128 v[170:173], v206 offset:1024
	ds_read_b128 v[174:177], v206 offset:2048
	ds_read_b128 v[178:181], v206 offset:3072
	ds_read_b128 v[182:185], v206 offset:4096
	ds_read_b128 v[208:211], v206 offset:5120
	ds_read_b128 v[214:217], v206 offset:6144
	ds_read_b128 v[218:221], v206 offset:7168
	global_load_lds_dwordx4 v[200:201], off
	v_lshl_add_u64 v[200:201], v[132:133], 0, s[30:31]
	s_add_i32 m0, s3, 0xe000
	s_nop 0
	global_load_lds_dwordx4 v[200:201], off
	s_waitcnt vmcnt(8)
	s_waitcnt lgkmcnt(0)
	s_barrier
	s_waitcnt lgkmcnt(0)
	v_mfma_f32_16x16x32_bf16 v[126:129], v[134:137], v[166:169], v[126:129]
	v_mfma_f32_16x16x32_bf16 v[126:129], v[138:141], v[170:173], v[126:129]
	v_mfma_f32_16x16x32_bf16 v[122:125], v[146:149], v[170:173], v[122:125]
	v_mfma_f32_16x16x32_bf16 v[122:125], v[142:145], v[166:169], v[122:125]
	v_mfma_f32_16x16x32_bf16 v[106:109], v[142:145], v[174:177], v[106:109]
	v_mfma_f32_16x16x32_bf16 v[106:109], v[146:149], v[178:181], v[106:109]
	v_mfma_f32_16x16x32_bf16 v[110:113], v[138:141], v[178:181], v[110:113]
	v_mfma_f32_16x16x32_bf16 v[110:113], v[134:137], v[174:177], v[110:113]
	v_mfma_f32_16x16x32_bf16 v[94:97], v[134:137], v[182:185], v[94:97]
	v_mfma_f32_16x16x32_bf16 v[94:97], v[138:141], v[208:211], v[94:97]
	v_mfma_f32_16x16x32_bf16 v[90:93], v[146:149], v[208:211], v[90:93]
	v_mfma_f32_16x16x32_bf16 v[90:93], v[142:145], v[182:185], v[90:93]
	v_mfma_f32_16x16x32_bf16 v[74:77], v[142:145], v[214:217], v[74:77]
	v_mfma_f32_16x16x32_bf16 v[74:77], v[146:149], v[218:221], v[74:77]
	v_mfma_f32_16x16x32_bf16 v[78:81], v[138:141], v[218:221], v[78:81]
	v_mfma_f32_16x16x32_bf16 v[78:81], v[134:137], v[214:217], v[78:81]
	v_mfma_f32_16x16x32_bf16 v[118:121], v[150:153], v[166:169], v[118:121]
	v_mfma_f32_16x16x32_bf16 v[118:121], v[154:157], v[170:173], v[118:121]
	v_mfma_f32_16x16x32_bf16 v[114:117], v[162:165], v[170:173], v[114:117]
	v_mfma_f32_16x16x32_bf16 v[114:117], v[158:161], v[166:169], v[114:117]
	v_mfma_f32_16x16x32_bf16 v[98:101], v[158:161], v[174:177], v[98:101]
	v_mfma_f32_16x16x32_bf16 v[98:101], v[162:165], v[178:181], v[98:101]
	v_mfma_f32_16x16x32_bf16 v[102:105], v[154:157], v[178:181], v[102:105]
	v_mfma_f32_16x16x32_bf16 v[102:105], v[150:153], v[174:177], v[102:105]
	v_mfma_f32_16x16x32_bf16 v[86:89], v[150:153], v[182:185], v[86:89]
	v_mfma_f32_16x16x32_bf16 v[86:89], v[154:157], v[208:211], v[86:89]
	v_mfma_f32_16x16x32_bf16 v[82:85], v[162:165], v[208:211], v[82:85]
	v_mfma_f32_16x16x32_bf16 v[82:85], v[158:161], v[182:185], v[82:85]
	v_mfma_f32_16x16x32_bf16 v[66:69], v[158:161], v[214:217], v[66:69]
	v_mfma_f32_16x16x32_bf16 v[66:69], v[162:165], v[218:221], v[66:69]
	v_mfma_f32_16x16x32_bf16 v[70:73], v[154:157], v[218:221], v[70:73]
	v_mfma_f32_16x16x32_bf16 v[70:73], v[150:153], v[214:217], v[70:73]
	s_barrier
	s_add_i32 s63, s52, s2
	v_lshl_add_u64 v[200:201], s[36:37], 0, v[188:189]
	s_mov_b32 m0, s63
	ds_read_b128 v[166:169], v206 offset:16384
	ds_read_b128 v[170:173], v206 offset:17408
	ds_read_b128 v[174:177], v206 offset:18432
	ds_read_b128 v[178:181], v206 offset:19456
	ds_read_b128 v[182:185], v206 offset:20480
	ds_read_b128 v[208:211], v206 offset:21504
	ds_read_b128 v[214:217], v206 offset:22528
	ds_read_b128 v[218:221], v206 offset:23552
	global_load_lds_dwordx4 v[200:201], off
	s_add_i32 m0, s63, 0x2000
	s_add_u32 s64, s36, 0x68000
	v_lshl_add_u64 v[222:223], s[36:37], 0, v[192:193]
	s_addc_u32 s65, s37, 0
	s_add_i32 s63, s53, s2
	global_load_lds_dwordx4 v[222:223], off
	s_mov_b32 m0, s63
	s_nop 0
	global_load_lds_dwordx4 v188, s[64:65]
	s_add_i32 m0, s63, 0x2000
	s_nop 0
	global_load_lds_dwordx4 v192, s[64:65]
	s_mov_b32 m0, s3
	s_nop 0
	global_load_lds_dwordx4 v186, s[38:39]
	s_mov_b32 m0, s33
	s_nop 0
	global_load_lds_dwordx4 v190, s[38:39]
	s_waitcnt vmcnt(8)
	s_waitcnt lgkmcnt(0)
	s_barrier
	s_waitcnt lgkmcnt(0)
	v_mfma_f32_16x16x32_bf16 v[62:65], v[134:137], v[166:169], v[62:65]
	v_mfma_f32_16x16x32_bf16 v[62:65], v[138:141], v[170:173], v[62:65]
	v_mfma_f32_16x16x32_bf16 v[58:61], v[146:149], v[170:173], v[58:61]
	v_mfma_f32_16x16x32_bf16 v[58:61], v[142:145], v[166:169], v[58:61]
	v_mfma_f32_16x16x32_bf16 v[42:45], v[142:145], v[174:177], v[42:45]
	v_mfma_f32_16x16x32_bf16 v[42:45], v[146:149], v[178:181], v[42:45]
	v_mfma_f32_16x16x32_bf16 v[46:49], v[138:141], v[178:181], v[46:49]
	v_mfma_f32_16x16x32_bf16 v[46:49], v[134:137], v[174:177], v[46:49]
	v_mfma_f32_16x16x32_bf16 v[30:33], v[134:137], v[182:185], v[30:33]
	v_mfma_f32_16x16x32_bf16 v[30:33], v[138:141], v[208:211], v[30:33]
	v_mfma_f32_16x16x32_bf16 v[26:29], v[146:149], v[208:211], v[26:29]
	v_mfma_f32_16x16x32_bf16 v[26:29], v[142:145], v[182:185], v[26:29]
	v_mfma_f32_16x16x32_bf16 v[10:13], v[142:145], v[214:217], v[10:13]
	v_mfma_f32_16x16x32_bf16 v[10:13], v[146:149], v[218:221], v[10:13]
	v_mfma_f32_16x16x32_bf16 v[14:17], v[138:141], v[218:221], v[14:17]
	v_mfma_f32_16x16x32_bf16 v[14:17], v[134:137], v[214:217], v[14:17]
	v_mfma_f32_16x16x32_bf16 v[54:57], v[150:153], v[166:169], v[54:57]
	v_mfma_f32_16x16x32_bf16 v[54:57], v[154:157], v[170:173], v[54:57]
	v_mfma_f32_16x16x32_bf16 v[50:53], v[162:165], v[170:173], v[50:53]
	v_mfma_f32_16x16x32_bf16 v[50:53], v[158:161], v[166:169], v[50:53]
	v_mfma_f32_16x16x32_bf16 v[34:37], v[158:161], v[174:177], v[34:37]
	v_mfma_f32_16x16x32_bf16 v[34:37], v[162:165], v[178:181], v[34:37]
	v_mfma_f32_16x16x32_bf16 v[38:41], v[154:157], v[178:181], v[38:41]
	v_mfma_f32_16x16x32_bf16 v[38:41], v[150:153], v[174:177], v[38:41]
	v_mfma_f32_16x16x32_bf16 v[22:25], v[150:153], v[182:185], v[22:25]
	v_mfma_f32_16x16x32_bf16 v[22:25], v[154:157], v[208:211], v[22:25]
	v_mfma_f32_16x16x32_bf16 v[18:21], v[162:165], v[208:211], v[18:21]
	v_mfma_f32_16x16x32_bf16 v[18:21], v[158:161], v[182:185], v[18:21]
	v_mfma_f32_16x16x32_bf16 v[2:5], v[158:161], v[214:217], v[2:5]
	v_mfma_f32_16x16x32_bf16 v[2:5], v[162:165], v[218:221], v[2:5]
	v_mfma_f32_16x16x32_bf16 v[6:9], v[154:157], v[218:221], v[6:9]
	v_mfma_f32_16x16x32_bf16 v[6:9], v[150:153], v[214:217], v[6:9]
	s_barrier
	s_add_i32 s63, 0, 0x18000
	s_add_i32 s64, 0, 0x1c000
	v_add_u32_e32 v146, s63, v202
	v_add_u32_e32 v162, s64, v202
	ds_read_b128 v[134:137], v146
	ds_read_b128 v[138:141], v146 offset:1024
	ds_read_b128 v[142:145], v146 offset:2048
	ds_read_b128 v[146:149], v146 offset:3072
	ds_read_b128 v[150:153], v162
	ds_read_b128 v[154:157], v162 offset:1024
	ds_read_b128 v[158:161], v162 offset:2048
	ds_read_b128 v[162:165], v162 offset:3072
	s_add_u32 s38, s38, 0x188000
	s_addc_u32 s39, s39, 0
	s_mov_b32 m0, s40
	ds_read_b128 v[166:169], v206 offset:32768
	ds_read_b128 v[170:173], v206 offset:33792
	ds_read_b128 v[174:177], v206 offset:34816
	ds_read_b128 v[178:181], v206 offset:35840
	ds_read_b128 v[182:185], v206 offset:36864
	ds_read_b128 v[208:211], v206 offset:37888
	ds_read_b128 v[214:217], v206 offset:38912
	ds_read_b128 v[218:221], v206 offset:39936
	global_load_lds_dwordx4 v186, s[38:39]
	v_lshl_add_u64 v[224:225], s[38:39], 0, v[190:191]
	s_mov_b32 m0, s41
	s_nop 0
	global_load_lds_dwordx4 v[224:225], off
	s_waitcnt vmcnt(8)
	s_waitcnt lgkmcnt(0)
	s_barrier
	s_waitcnt lgkmcnt(0)
	v_mfma_f32_16x16x32_bf16 v[126:129], v[134:137], v[166:169], v[126:129]
	v_mfma_f32_16x16x32_bf16 v[126:129], v[138:141], v[170:173], v[126:129]
	v_mfma_f32_16x16x32_bf16 v[122:125], v[146:149], v[170:173], v[122:125]
	v_mfma_f32_16x16x32_bf16 v[122:125], v[142:145], v[166:169], v[122:125]
	v_mfma_f32_16x16x32_bf16 v[106:109], v[142:145], v[174:177], v[106:109]
	v_mfma_f32_16x16x32_bf16 v[106:109], v[146:149], v[178:181], v[106:109]
	v_mfma_f32_16x16x32_bf16 v[110:113], v[138:141], v[178:181], v[110:113]
	v_mfma_f32_16x16x32_bf16 v[110:113], v[134:137], v[174:177], v[110:113]
	v_mfma_f32_16x16x32_bf16 v[94:97], v[134:137], v[182:185], v[94:97]
	v_mfma_f32_16x16x32_bf16 v[94:97], v[138:141], v[208:211], v[94:97]
	v_mfma_f32_16x16x32_bf16 v[90:93], v[146:149], v[208:211], v[90:93]
	v_mfma_f32_16x16x32_bf16 v[90:93], v[142:145], v[182:185], v[90:93]
	v_mfma_f32_16x16x32_bf16 v[74:77], v[142:145], v[214:217], v[74:77]
	v_mfma_f32_16x16x32_bf16 v[74:77], v[146:149], v[218:221], v[74:77]
	v_mfma_f32_16x16x32_bf16 v[78:81], v[138:141], v[218:221], v[78:81]
	v_mfma_f32_16x16x32_bf16 v[78:81], v[134:137], v[214:217], v[78:81]
	v_mfma_f32_16x16x32_bf16 v[118:121], v[150:153], v[166:169], v[118:121]
	v_mfma_f32_16x16x32_bf16 v[118:121], v[154:157], v[170:173], v[118:121]
	v_mfma_f32_16x16x32_bf16 v[114:117], v[162:165], v[170:173], v[114:117]
	v_mfma_f32_16x16x32_bf16 v[114:117], v[158:161], v[166:169], v[114:117]
	v_mfma_f32_16x16x32_bf16 v[98:101], v[158:161], v[174:177], v[98:101]
	v_mfma_f32_16x16x32_bf16 v[98:101], v[162:165], v[178:181], v[98:101]
	v_mfma_f32_16x16x32_bf16 v[102:105], v[154:157], v[178:181], v[102:105]
	v_mfma_f32_16x16x32_bf16 v[102:105], v[150:153], v[174:177], v[102:105]
	v_mfma_f32_16x16x32_bf16 v[86:89], v[150:153], v[182:185], v[86:89]
	v_mfma_f32_16x16x32_bf16 v[86:89], v[154:157], v[208:211], v[86:89]
	v_mfma_f32_16x16x32_bf16 v[82:85], v[162:165], v[208:211], v[82:85]
	v_mfma_f32_16x16x32_bf16 v[82:85], v[158:161], v[182:185], v[82:85]
	v_mfma_f32_16x16x32_bf16 v[66:69], v[158:161], v[214:217], v[66:69]
	v_mfma_f32_16x16x32_bf16 v[66:69], v[162:165], v[218:221], v[66:69]
	v_mfma_f32_16x16x32_bf16 v[70:73], v[154:157], v[218:221], v[70:73]
	v_mfma_f32_16x16x32_bf16 v[70:73], v[150:153], v[214:217], v[70:73]
	s_barrier
	s_add_i32 s38, s63, s2
	v_lshl_add_u64 v[200:201], v[200:201], 0, s[12:13]
	s_mov_b32 m0, s38
	ds_read_b128 v[166:169], v206 offset:49152
	ds_read_b128 v[170:173], v206 offset:50176
	ds_read_b128 v[174:177], v206 offset:51200
	ds_read_b128 v[178:181], v206 offset:52224
	ds_read_b128 v[182:185], v206 offset:53248
	ds_read_b128 v[208:211], v206 offset:54272
	ds_read_b128 v[214:217], v206 offset:55296
	ds_read_b128 v[218:221], v206 offset:56320
	global_load_lds_dwordx4 v[200:201], off
	s_add_i32 m0, s38, 0x2000
	s_add_u32 s36, s36, 0x68080
	v_lshl_add_u64 v[200:201], v[222:223], 0, s[12:13]
	s_addc_u32 s37, s37, 0
	s_add_i32 s38, s64, s2
	global_load_lds_dwordx4 v[200:201], off
	s_mov_b32 m0, s38
	s_nop 0
	global_load_lds_dwordx4 v188, s[36:37]
	s_add_i32 m0, s38, 0x2000
	s_nop 0
	global_load_lds_dwordx4 v192, s[36:37]
	s_mov_b32 m0, s50
	s_nop 0
	global_load_lds_dwordx4 v186, s[34:35]
	s_mov_b32 m0, s51
	s_nop 0
	global_load_lds_dwordx4 v190, s[34:35]
	s_waitcnt vmcnt(8)
	s_waitcnt lgkmcnt(0)
	s_barrier
	s_waitcnt lgkmcnt(0)
	v_mfma_f32_16x16x32_bf16 v[62:65], v[134:137], v[166:169], v[62:65]
	v_mfma_f32_16x16x32_bf16 v[62:65], v[138:141], v[170:173], v[62:65]
	v_mfma_f32_16x16x32_bf16 v[58:61], v[146:149], v[170:173], v[58:61]
	v_mfma_f32_16x16x32_bf16 v[58:61], v[142:145], v[166:169], v[58:61]
	v_mfma_f32_16x16x32_bf16 v[42:45], v[142:145], v[174:177], v[42:45]
	v_mfma_f32_16x16x32_bf16 v[42:45], v[146:149], v[178:181], v[42:45]
	v_mfma_f32_16x16x32_bf16 v[46:49], v[138:141], v[178:181], v[46:49]
	v_mfma_f32_16x16x32_bf16 v[46:49], v[134:137], v[174:177], v[46:49]
	v_mfma_f32_16x16x32_bf16 v[30:33], v[134:137], v[182:185], v[30:33]
	v_mfma_f32_16x16x32_bf16 v[30:33], v[138:141], v[208:211], v[30:33]
	v_mfma_f32_16x16x32_bf16 v[26:29], v[146:149], v[208:211], v[26:29]
	v_mfma_f32_16x16x32_bf16 v[26:29], v[142:145], v[182:185], v[26:29]
	v_mfma_f32_16x16x32_bf16 v[10:13], v[142:145], v[214:217], v[10:13]
	v_mfma_f32_16x16x32_bf16 v[10:13], v[146:149], v[218:221], v[10:13]
	v_mfma_f32_16x16x32_bf16 v[14:17], v[138:141], v[218:221], v[14:17]
	v_mfma_f32_16x16x32_bf16 v[14:17], v[134:137], v[214:217], v[14:17]
	v_mfma_f32_16x16x32_bf16 v[54:57], v[150:153], v[166:169], v[54:57]
	v_mfma_f32_16x16x32_bf16 v[54:57], v[154:157], v[170:173], v[54:57]
	v_mfma_f32_16x16x32_bf16 v[50:53], v[162:165], v[170:173], v[50:53]
	v_mfma_f32_16x16x32_bf16 v[50:53], v[158:161], v[166:169], v[50:53]
	v_mfma_f32_16x16x32_bf16 v[34:37], v[158:161], v[174:177], v[34:37]
	v_mfma_f32_16x16x32_bf16 v[34:37], v[162:165], v[178:181], v[34:37]
	v_mfma_f32_16x16x32_bf16 v[38:41], v[154:157], v[178:181], v[38:41]
	v_mfma_f32_16x16x32_bf16 v[38:41], v[150:153], v[174:177], v[38:41]
	v_mfma_f32_16x16x32_bf16 v[22:25], v[150:153], v[182:185], v[22:25]
	v_mfma_f32_16x16x32_bf16 v[22:25], v[154:157], v[208:211], v[22:25]
	v_mfma_f32_16x16x32_bf16 v[18:21], v[162:165], v[208:211], v[18:21]
	v_mfma_f32_16x16x32_bf16 v[18:21], v[158:161], v[182:185], v[18:21]
	v_mfma_f32_16x16x32_bf16 v[2:5], v[158:161], v[214:217], v[2:5]
	v_mfma_f32_16x16x32_bf16 v[2:5], v[162:165], v[218:221], v[2:5]
	v_mfma_f32_16x16x32_bf16 v[6:9], v[154:157], v[218:221], v[6:9]
	v_mfma_f32_16x16x32_bf16 v[6:9], v[150:153], v[214:217], v[6:9]
	s_barrier
	s_add_i32 s62, s62, 2
	s_add_u32 s30, s30, 0x100
	s_addc_u32 s31, s31, 0
	s_cmp_gt_u32 s62, 21
	s_cbranch_scc0 .LBB0_434
	s_and_b64 vcc, exec, s[14:15]
	s_cbranch_vccz .LBB0_437
	s_barrier

.LBB0_519:
	s_add_i32 s39, s56, 0xfffe8000
	s_and_b32 s38, s36, 0x100
	s_and_b32 s39, s39, 0x3e0000
	s_or_b32 s38, s38, s39
	s_add_u32 s57, s34, s38
	s_addc_u32 s59, s35, 0
	s_add_u32 s38, s36, 0x100
	s_addc_u32 s39, s37, 0
	s_add_i32 s41, s56, 0xffff8000
	s_and_b32 s40, s38, 0x100
	s_and_b32 s41, s41, 0x7e0000
	s_or_b32 s40, s41, s40
	s_add_u32 s40, s34, s40
	s_addc_u32 s41, s35, 0
	s_add_u32 s58, s53, s36
	s_addc_u32 s37, s54, s37
	s_add_i32 s42, s36, 0x180
	s_and_b32 s42, s42, 0x180
	s_and_b32 s43, s56, 0x7e0000
	s_or_b32 s42, s43, s42
	s_add_u32 s60, s34, s42
	s_addc_u32 s61, s35, 0
	s_cmpk_eq_i32 s36, 0x3f00
	s_cselect_b32 s43, s1, s41
	s_cselect_b32 s42, s21, s40
	s_cselect_b32 s41, s23, s37
	s_cselect_b32 s40, s22, s58
	s_cselect_b32 s37, s52, s61
	s_cselect_b32 s36, s31, s60
	s_add_i32 s60, 0, 0x10000
	v_add_u32_e32 v1, s60, v199
	ds_read_b128 v[130:133], v1
	ds_read_b128 v[134:137], v1 offset:1024
	ds_read_b128 v[138:141], v1 offset:2048
	ds_read_b128 v[142:145], v1 offset:3072
	ds_read_b128 v[146:149], v201
	ds_read_b128 v[150:153], v201 offset:1024
	ds_read_b128 v[154:157], v201 offset:2048
	ds_read_b128 v[158:161], v201 offset:3072
	s_add_u32 s58, s57, 0x10080
	s_addc_u32 s59, s59, 0
	s_add_i32 m0, s3, 0xc000
	ds_read_b128 v[162:165], v202
	ds_read_b128 v[166:169], v202 offset:1024
	ds_read_b128 v[170:173], v202 offset:2048
	ds_read_b128 v[174:177], v202 offset:3072
	ds_read_b128 v[186:189], v202 offset:4096
	ds_read_b128 v[190:193], v202 offset:5120
	ds_read_b128 v[194:197], v202 offset:6144
	ds_read_b128 v[204:207], v202 offset:7168
	global_load_lds_dwordx4 v178, s[58:59]
	s_add_i32 m0, s3, 0xe000
	s_nop 0
	global_load_lds_dwordx4 v182, s[58:59]
	s_waitcnt vmcnt(8)
	s_waitcnt lgkmcnt(0)
	s_barrier
	s_waitcnt lgkmcnt(0)
	v_mfma_f32_16x16x32_bf16 v[126:129], v[130:133], v[162:165], v[126:129]
	v_mfma_f32_16x16x32_bf16 v[126:129], v[134:137], v[166:169], v[126:129]
	v_mfma_f32_16x16x32_bf16 v[122:125], v[142:145], v[166:169], v[122:125]
	v_mfma_f32_16x16x32_bf16 v[122:125], v[138:141], v[162:165], v[122:125]
	v_mfma_f32_16x16x32_bf16 v[106:109], v[138:141], v[170:173], v[106:109]
	v_mfma_f32_16x16x32_bf16 v[106:109], v[142:145], v[174:177], v[106:109]
	v_mfma_f32_16x16x32_bf16 v[110:113], v[134:137], v[174:177], v[110:113]
	v_mfma_f32_16x16x32_bf16 v[110:113], v[130:133], v[170:173], v[110:113]
	v_mfma_f32_16x16x32_bf16 v[94:97], v[130:133], v[186:189], v[94:97]
	v_mfma_f32_16x16x32_bf16 v[94:97], v[134:137], v[190:193], v[94:97]
	v_mfma_f32_16x16x32_bf16 v[90:93], v[142:145], v[190:193], v[90:93]
	v_mfma_f32_16x16x32_bf16 v[90:93], v[138:141], v[186:189], v[90:93]
	v_mfma_f32_16x16x32_bf16 v[74:77], v[138:141], v[194:197], v[74:77]
	v_mfma_f32_16x16x32_bf16 v[74:77], v[142:145], v[204:207], v[74:77]
	v_mfma_f32_16x16x32_bf16 v[78:81], v[134:137], v[204:207], v[78:81]
	v_mfma_f32_16x16x32_bf16 v[78:81], v[130:133], v[194:197], v[78:81]
	v_mfma_f32_16x16x32_bf16 v[118:121], v[146:149], v[162:165], v[118:121]
	v_mfma_f32_16x16x32_bf16 v[118:121], v[150:153], v[166:169], v[118:121]
	v_mfma_f32_16x16x32_bf16 v[114:117], v[158:161], v[166:169], v[114:117]
	v_mfma_f32_16x16x32_bf16 v[114:117], v[154:157], v[162:165], v[114:117]
	v_mfma_f32_16x16x32_bf16 v[98:101], v[154:157], v[170:173], v[98:101]
	v_mfma_f32_16x16x32_bf16 v[98:101], v[158:161], v[174:177], v[98:101]
	v_mfma_f32_16x16x32_bf16 v[102:105], v[150:153], v[174:177], v[102:105]
	v_mfma_f32_16x16x32_bf16 v[102:105], v[146:149], v[170:173], v[102:105]
	v_mfma_f32_16x16x32_bf16 v[86:89], v[146:149], v[186:189], v[86:89]
	v_mfma_f32_16x16x32_bf16 v[86:89], v[150:153], v[190:193], v[86:89]
	v_mfma_f32_16x16x32_bf16 v[82:85], v[158:161], v[190:193], v[82:85]
	v_mfma_f32_16x16x32_bf16 v[82:85], v[154:157], v[186:189], v[82:85]
	v_mfma_f32_16x16x32_bf16 v[66:69], v[154:157], v[194:197], v[66:69]
	v_mfma_f32_16x16x32_bf16 v[66:69], v[158:161], v[204:207], v[66:69]
	v_mfma_f32_16x16x32_bf16 v[70:73], v[150:153], v[204:207], v[70:73]
	v_mfma_f32_16x16x32_bf16 v[70:73], v[146:149], v[194:197], v[70:73]
	s_barrier
	s_add_i32 s57, s60, s2
	v_lshl_add_u64 v[208:209], s[40:41], 0, v[180:181]
	s_mov_b32 m0, s57
	ds_read_b128 v[162:165], v202 offset:16384
	ds_read_b128 v[166:169], v202 offset:17408
	ds_read_b128 v[170:173], v202 offset:18432
	ds_read_b128 v[174:177], v202 offset:19456
	ds_read_b128 v[186:189], v202 offset:20480
	ds_read_b128 v[190:193], v202 offset:21504
	ds_read_b128 v[194:197], v202 offset:22528
	ds_read_b128 v[204:207], v202 offset:23552
	global_load_lds_dwordx4 v[208:209], off
	s_add_i32 m0, s57, 0x2000
	s_add_u32 s58, s40, 0x208000
	v_lshl_add_u64 v[210:211], s[40:41], 0, v[184:185]
	s_addc_u32 s59, s41, 0
	s_add_i32 s57, s49, s2
	global_load_lds_dwordx4 v[210:211], off
	s_mov_b32 m0, s57
	s_nop 0
	global_load_lds_dwordx4 v180, s[58:59]
	s_add_i32 m0, s57, 0x2000
	s_nop 0
	global_load_lds_dwordx4 v184, s[58:59]
	s_mov_b32 m0, s3
	s_nop 0
	global_load_lds_dwordx4 v178, s[42:43]
	s_mov_b32 m0, s33
	s_nop 0
	global_load_lds_dwordx4 v182, s[42:43]
	s_waitcnt vmcnt(8)
	s_waitcnt lgkmcnt(0)
	s_barrier
	s_waitcnt lgkmcnt(0)
	v_mfma_f32_16x16x32_bf16 v[62:65], v[130:133], v[162:165], v[62:65]
	v_mfma_f32_16x16x32_bf16 v[62:65], v[134:137], v[166:169], v[62:65]
	v_mfma_f32_16x16x32_bf16 v[58:61], v[142:145], v[166:169], v[58:61]
	v_mfma_f32_16x16x32_bf16 v[58:61], v[138:141], v[162:165], v[58:61]
	v_mfma_f32_16x16x32_bf16 v[42:45], v[138:141], v[170:173], v[42:45]
	v_mfma_f32_16x16x32_bf16 v[42:45], v[142:145], v[174:177], v[42:45]
	v_mfma_f32_16x16x32_bf16 v[46:49], v[134:137], v[174:177], v[46:49]
	v_mfma_f32_16x16x32_bf16 v[46:49], v[130:133], v[170:173], v[46:49]
	v_mfma_f32_16x16x32_bf16 v[30:33], v[130:133], v[186:189], v[30:33]
	v_mfma_f32_16x16x32_bf16 v[30:33], v[134:137], v[190:193], v[30:33]
	v_mfma_f32_16x16x32_bf16 v[26:29], v[142:145], v[190:193], v[26:29]
	v_mfma_f32_16x16x32_bf16 v[26:29], v[138:141], v[186:189], v[26:29]
	v_mfma_f32_16x16x32_bf16 v[10:13], v[138:141], v[194:197], v[10:13]
	v_mfma_f32_16x16x32_bf16 v[10:13], v[142:145], v[204:207], v[10:13]
	v_mfma_f32_16x16x32_bf16 v[14:17], v[134:137], v[204:207], v[14:17]
	v_mfma_f32_16x16x32_bf16 v[14:17], v[130:133], v[194:197], v[14:17]
	v_mfma_f32_16x16x32_bf16 v[54:57], v[146:149], v[162:165], v[54:57]
	v_mfma_f32_16x16x32_bf16 v[54:57], v[150:153], v[166:169], v[54:57]
	v_mfma_f32_16x16x32_bf16 v[50:53], v[158:161], v[166:169], v[50:53]
	v_mfma_f32_16x16x32_bf16 v[50:53], v[154:157], v[162:165], v[50:53]
	v_mfma_f32_16x16x32_bf16 v[34:37], v[154:157], v[170:173], v[34:37]
	v_mfma_f32_16x16x32_bf16 v[34:37], v[158:161], v[174:177], v[34:37]
	v_mfma_f32_16x16x32_bf16 v[38:41], v[150:153], v[174:177], v[38:41]
	v_mfma_f32_16x16x32_bf16 v[38:41], v[146:149], v[170:173], v[38:41]
	v_mfma_f32_16x16x32_bf16 v[22:25], v[146:149], v[186:189], v[22:25]
	v_mfma_f32_16x16x32_bf16 v[22:25], v[150:153], v[190:193], v[22:25]
	v_mfma_f32_16x16x32_bf16 v[18:21], v[158:161], v[190:193], v[18:21]
	v_mfma_f32_16x16x32_bf16 v[18:21], v[154:157], v[186:189], v[18:21]
	v_mfma_f32_16x16x32_bf16 v[2:5], v[154:157], v[194:197], v[2:5]
	v_mfma_f32_16x16x32_bf16 v[2:5], v[158:161], v[204:207], v[2:5]
	v_mfma_f32_16x16x32_bf16 v[6:9], v[150:153], v[204:207], v[6:9]
	v_mfma_f32_16x16x32_bf16 v[6:9], v[146:149], v[194:197], v[6:9]
	s_barrier
	s_add_i32 s57, 0, 0x18000
	v_add_u32_e32 v1, s57, v199
	s_add_i32 s58, 0, 0x1c000
	ds_read_b128 v[130:133], v1
	ds_read_b128 v[134:137], v1 offset:1024
	ds_read_b128 v[138:141], v1 offset:2048
	ds_read_b128 v[142:145], v1 offset:3072
	v_add_u32_e32 v1, s58, v199
	ds_read_b128 v[146:149], v1
	ds_read_b128 v[150:153], v1 offset:1024
	ds_read_b128 v[154:157], v1 offset:2048
	ds_read_b128 v[158:161], v1 offset:3072
	s_add_u32 s42, s42, 0x10000
	s_addc_u32 s43, s43, 0
	s_mov_b32 m0, s44
	ds_read_b128 v[162:165], v202 offset:32768
	ds_read_b128 v[166:169], v202 offset:33792
	ds_read_b128 v[170:173], v202 offset:34816
	ds_read_b128 v[174:177], v202 offset:35840
	ds_read_b128 v[186:189], v202 offset:36864
	ds_read_b128 v[190:193], v202 offset:37888
	ds_read_b128 v[194:197], v202 offset:38912
	ds_read_b128 v[204:207], v202 offset:39936
	global_load_lds_dwordx4 v178, s[42:43]
	v_lshl_add_u64 v[214:215], s[42:43], 0, v[182:183]
	s_mov_b32 m0, s45
	s_nop 0
	global_load_lds_dwordx4 v[214:215], off
	s_waitcnt vmcnt(8)
	s_waitcnt lgkmcnt(0)
	s_barrier
	s_waitcnt lgkmcnt(0)
	v_mfma_f32_16x16x32_bf16 v[126:129], v[130:133], v[162:165], v[126:129]
	v_mfma_f32_16x16x32_bf16 v[126:129], v[134:137], v[166:169], v[126:129]
	v_mfma_f32_16x16x32_bf16 v[122:125], v[142:145], v[166:169], v[122:125]
	v_mfma_f32_16x16x32_bf16 v[122:125], v[138:141], v[162:165], v[122:125]
	v_mfma_f32_16x16x32_bf16 v[106:109], v[138:141], v[170:173], v[106:109]
	v_mfma_f32_16x16x32_bf16 v[106:109], v[142:145], v[174:177], v[106:109]
	v_mfma_f32_16x16x32_bf16 v[110:113], v[134:137], v[174:177], v[110:113]
	v_mfma_f32_16x16x32_bf16 v[110:113], v[130:133], v[170:173], v[110:113]
	v_mfma_f32_16x16x32_bf16 v[94:97], v[130:133], v[186:189], v[94:97]
	v_mfma_f32_16x16x32_bf16 v[94:97], v[134:137], v[190:193], v[94:97]
	v_mfma_f32_16x16x32_bf16 v[90:93], v[142:145], v[190:193], v[90:93]
	v_mfma_f32_16x16x32_bf16 v[90:93], v[138:141], v[186:189], v[90:93]
	v_mfma_f32_16x16x32_bf16 v[74:77], v[138:141], v[194:197], v[74:77]
	v_mfma_f32_16x16x32_bf16 v[74:77], v[142:145], v[204:207], v[74:77]
	v_mfma_f32_16x16x32_bf16 v[78:81], v[134:137], v[204:207], v[78:81]
	v_mfma_f32_16x16x32_bf16 v[78:81], v[130:133], v[194:197], v[78:81]
	v_mfma_f32_16x16x32_bf16 v[118:121], v[146:149], v[162:165], v[118:121]
	v_mfma_f32_16x16x32_bf16 v[118:121], v[150:153], v[166:169], v[118:121]
	v_mfma_f32_16x16x32_bf16 v[114:117], v[158:161], v[166:169], v[114:117]
	v_mfma_f32_16x16x32_bf16 v[114:117], v[154:157], v[162:165], v[114:117]
	v_mfma_f32_16x16x32_bf16 v[98:101], v[154:157], v[170:173], v[98:101]
	v_mfma_f32_16x16x32_bf16 v[98:101], v[158:161], v[174:177], v[98:101]
	v_mfma_f32_16x16x32_bf16 v[102:105], v[150:153], v[174:177], v[102:105]
	v_mfma_f32_16x16x32_bf16 v[102:105], v[146:149], v[170:173], v[102:105]
	v_mfma_f32_16x16x32_bf16 v[86:89], v[146:149], v[186:189], v[86:89]
	v_mfma_f32_16x16x32_bf16 v[86:89], v[150:153], v[190:193], v[86:89]
	v_mfma_f32_16x16x32_bf16 v[82:85], v[158:161], v[190:193], v[82:85]
	v_mfma_f32_16x16x32_bf16 v[82:85], v[154:157], v[186:189], v[82:85]
	v_mfma_f32_16x16x32_bf16 v[66:69], v[154:157], v[194:197], v[66:69]
	v_mfma_f32_16x16x32_bf16 v[66:69], v[158:161], v[204:207], v[66:69]
	v_mfma_f32_16x16x32_bf16 v[70:73], v[150:153], v[204:207], v[70:73]
	v_mfma_f32_16x16x32_bf16 v[70:73], v[146:149], v[194:197], v[70:73]
	s_barrier
	s_add_i32 s42, s57, s2
	v_lshl_add_u64 v[208:209], v[208:209], 0, s[16:17]
	s_mov_b32 m0, s42
	ds_read_b128 v[162:165], v202 offset:49152
	ds_read_b128 v[166:169], v202 offset:50176
	ds_read_b128 v[170:173], v202 offset:51200
	ds_read_b128 v[174:177], v202 offset:52224
	ds_read_b128 v[186:189], v202 offset:53248
	ds_read_b128 v[190:193], v202 offset:54272
	ds_read_b128 v[194:197], v202 offset:55296
	ds_read_b128 v[204:207], v202 offset:56320
	global_load_lds_dwordx4 v[208:209], off
	s_add_i32 m0, s42, 0x2000
	s_add_u32 s40, s40, 0x208080
	v_lshl_add_u64 v[208:209], v[210:211], 0, s[16:17]
	s_addc_u32 s41, s41, 0
	s_add_i32 s42, s58, s2
	global_load_lds_dwordx4 v[208:209], off
	s_mov_b32 m0, s42
	s_nop 0
	global_load_lds_dwordx4 v180, s[40:41]
	s_add_i32 m0, s42, 0x2000
	s_nop 0
	global_load_lds_dwordx4 v184, s[40:41]
	s_mov_b32 m0, s47
	s_nop 0
	global_load_lds_dwordx4 v178, s[36:37]
	v_lshl_add_u64 v[208:209], s[36:37], 0, v[182:183]
	s_mov_b32 m0, s48
	s_nop 0
	global_load_lds_dwordx4 v[208:209], off
	s_waitcnt vmcnt(8)
	s_waitcnt lgkmcnt(0)
	s_barrier
	s_waitcnt lgkmcnt(0)
	v_mfma_f32_16x16x32_bf16 v[62:65], v[130:133], v[162:165], v[62:65]
	v_mfma_f32_16x16x32_bf16 v[62:65], v[134:137], v[166:169], v[62:65]
	v_mfma_f32_16x16x32_bf16 v[58:61], v[142:145], v[166:169], v[58:61]
	v_mfma_f32_16x16x32_bf16 v[58:61], v[138:141], v[162:165], v[58:61]
	v_mfma_f32_16x16x32_bf16 v[42:45], v[138:141], v[170:173], v[42:45]
	v_mfma_f32_16x16x32_bf16 v[42:45], v[142:145], v[174:177], v[42:45]
	v_mfma_f32_16x16x32_bf16 v[46:49], v[134:137], v[174:177], v[46:49]
	v_mfma_f32_16x16x32_bf16 v[46:49], v[130:133], v[170:173], v[46:49]
	v_mfma_f32_16x16x32_bf16 v[30:33], v[130:133], v[186:189], v[30:33]
	v_mfma_f32_16x16x32_bf16 v[30:33], v[134:137], v[190:193], v[30:33]
	v_mfma_f32_16x16x32_bf16 v[26:29], v[142:145], v[190:193], v[26:29]
	v_mfma_f32_16x16x32_bf16 v[26:29], v[138:141], v[186:189], v[26:29]
	v_mfma_f32_16x16x32_bf16 v[10:13], v[138:141], v[194:197], v[10:13]
	v_mfma_f32_16x16x32_bf16 v[10:13], v[142:145], v[204:207], v[10:13]
	v_mfma_f32_16x16x32_bf16 v[14:17], v[134:137], v[204:207], v[14:17]
	v_mfma_f32_16x16x32_bf16 v[14:17], v[130:133], v[194:197], v[14:17]
	v_mfma_f32_16x16x32_bf16 v[54:57], v[146:149], v[162:165], v[54:57]
	v_mfma_f32_16x16x32_bf16 v[54:57], v[150:153], v[166:169], v[54:57]
	v_mfma_f32_16x16x32_bf16 v[50:53], v[158:161], v[166:169], v[50:53]
	v_mfma_f32_16x16x32_bf16 v[50:53], v[154:157], v[162:165], v[50:53]
	v_mfma_f32_16x16x32_bf16 v[34:37], v[154:157], v[170:173], v[34:37]
	v_mfma_f32_16x16x32_bf16 v[34:37], v[158:161], v[174:177], v[34:37]
	v_mfma_f32_16x16x32_bf16 v[38:41], v[150:153], v[174:177], v[38:41]
	v_mfma_f32_16x16x32_bf16 v[38:41], v[146:149], v[170:173], v[38:41]
	v_mfma_f32_16x16x32_bf16 v[22:25], v[146:149], v[186:189], v[22:25]
	v_mfma_f32_16x16x32_bf16 v[22:25], v[150:153], v[190:193], v[22:25]
	v_mfma_f32_16x16x32_bf16 v[18:21], v[158:161], v[190:193], v[18:21]
	v_mfma_f32_16x16x32_bf16 v[18:21], v[154:157], v[186:189], v[18:21]
	v_mfma_f32_16x16x32_bf16 v[2:5], v[154:157], v[194:197], v[2:5]
	v_mfma_f32_16x16x32_bf16 v[2:5], v[158:161], v[204:207], v[2:5]
	v_mfma_f32_16x16x32_bf16 v[6:9], v[150:153], v[204:207], v[6:9]
	v_mfma_f32_16x16x32_bf16 v[6:9], v[146:149], v[194:197], v[6:9]
	s_barrier
	s_add_i32 s55, s55, 2
	s_add_i32 s56, s56, 0x10000
	s_cmpk_gt_u32 s55, 0x7d
	s_mov_b64 s[36:37], s[38:39]
	s_cbranch_scc0 .LBB0_519
	s_and_b64 vcc, exec, s[18:19]
	s_cbranch_vccz .LBB0_522
	s_barrier

.LBB0_612:
	ds_read_b128 v[166:169], v152
	ds_read_b128 v[170:173], v152 offset:1024
	ds_read_b128 v[174:177], v152 offset:2048
	ds_read_b128 v[178:181], v152 offset:3072
	ds_read_b128 v[182:185], v153
	ds_read_b128 v[186:189], v153 offset:1024
	ds_read_b128 v[190:193], v153 offset:2048
	ds_read_b128 v[194:197], v153 offset:3072
	s_add_u32 s26, s4, s22
	s_addc_u32 s27, s5, s23
	s_add_u32 s30, s26, 0x100
	s_addc_u32 s31, s27, 0
	s_add_u32 s28, s52, s22
	s_addc_u32 s29, s53, s23
	s_add_u32 s26, s26, 0x180
	s_addc_u32 s27, s27, 0
	s_cmpk_eq_i32 s22, 0x1f00
	s_cselect_b32 s27, s51, s27
	s_cselect_b32 s26, s50, s26
	s_cselect_b32 s29, s21, s29
	s_cselect_b32 s28, s20, s28
	s_cselect_b32 s31, s19, s31
	s_cselect_b32 s30, s18, s30
	s_mov_b32 m0, s37
	v_lshl_add_u64 v[210:211], v[148:149], 0, s[22:23]
	ds_read_b128 v[198:201], v154
	ds_read_b128 v[202:205], v154 offset:1024
	ds_read_b128 v[206:209], v154 offset:2048
	ds_read_b128 v[214:217], v154 offset:3072
	ds_read_b128 v[218:221], v154 offset:4096
	ds_read_b128 v[222:225], v154 offset:5120
	ds_read_b128 v[226:229], v154 offset:6144
	ds_read_b128 v[230:233], v154 offset:7168
	global_load_lds_dwordx4 v[210:211], off
	v_lshl_add_u64 v[210:211], v[150:151], 0, s[22:23]
	s_mov_b32 m0, s38
	s_nop 0
	global_load_lds_dwordx4 v[210:211], off
	s_waitcnt vmcnt(8)
	s_waitcnt lgkmcnt(0)
	s_barrier
	s_waitcnt lgkmcnt(0)
	v_mfma_f32_16x16x32_bf16 v[126:129], v[166:169], v[198:201], v[126:129]
	v_mfma_f32_16x16x32_bf16 v[126:129], v[170:173], v[202:205], v[126:129]
	v_mfma_f32_16x16x32_bf16 v[122:125], v[178:181], v[202:205], v[122:125]
	v_mfma_f32_16x16x32_bf16 v[122:125], v[174:177], v[198:201], v[122:125]
	v_mfma_f32_16x16x32_bf16 v[106:109], v[174:177], v[206:209], v[106:109]
	v_mfma_f32_16x16x32_bf16 v[106:109], v[178:181], v[214:217], v[106:109]
	v_mfma_f32_16x16x32_bf16 v[110:113], v[170:173], v[214:217], v[110:113]
	v_mfma_f32_16x16x32_bf16 v[110:113], v[166:169], v[206:209], v[110:113]
	v_mfma_f32_16x16x32_bf16 v[94:97], v[166:169], v[218:221], v[94:97]
	v_mfma_f32_16x16x32_bf16 v[94:97], v[170:173], v[222:225], v[94:97]
	v_mfma_f32_16x16x32_bf16 v[90:93], v[178:181], v[222:225], v[90:93]
	v_mfma_f32_16x16x32_bf16 v[90:93], v[174:177], v[218:221], v[90:93]
	v_mfma_f32_16x16x32_bf16 v[74:77], v[174:177], v[226:229], v[74:77]
	v_mfma_f32_16x16x32_bf16 v[74:77], v[178:181], v[230:233], v[74:77]
	v_mfma_f32_16x16x32_bf16 v[78:81], v[170:173], v[230:233], v[78:81]
	v_mfma_f32_16x16x32_bf16 v[78:81], v[166:169], v[226:229], v[78:81]
	v_mfma_f32_16x16x32_bf16 v[118:121], v[182:185], v[198:201], v[118:121]
	v_mfma_f32_16x16x32_bf16 v[118:121], v[186:189], v[202:205], v[118:121]
	v_mfma_f32_16x16x32_bf16 v[114:117], v[194:197], v[202:205], v[114:117]
	v_mfma_f32_16x16x32_bf16 v[114:117], v[190:193], v[198:201], v[114:117]
	v_mfma_f32_16x16x32_bf16 v[98:101], v[190:193], v[206:209], v[98:101]
	v_mfma_f32_16x16x32_bf16 v[98:101], v[194:197], v[214:217], v[98:101]
	v_mfma_f32_16x16x32_bf16 v[102:105], v[186:189], v[214:217], v[102:105]
	v_mfma_f32_16x16x32_bf16 v[102:105], v[182:185], v[206:209], v[102:105]
	v_mfma_f32_16x16x32_bf16 v[86:89], v[182:185], v[218:221], v[86:89]
	v_mfma_f32_16x16x32_bf16 v[86:89], v[186:189], v[222:225], v[86:89]
	v_mfma_f32_16x16x32_bf16 v[82:85], v[194:197], v[222:225], v[82:85]
	v_mfma_f32_16x16x32_bf16 v[82:85], v[190:193], v[218:221], v[82:85]
	v_mfma_f32_16x16x32_bf16 v[66:69], v[190:193], v[226:229], v[66:69]
	v_mfma_f32_16x16x32_bf16 v[66:69], v[194:197], v[230:233], v[66:69]
	v_mfma_f32_16x16x32_bf16 v[70:73], v[186:189], v[230:233], v[70:73]
	v_mfma_f32_16x16x32_bf16 v[70:73], v[182:185], v[226:229], v[70:73]
	s_barrier
	s_mov_b32 m0, s39
	v_lshl_add_u64 v[210:211], s[28:29], 0, v[132:133]
	s_add_u32 s56, s28, 0x108000
	ds_read_b128 v[198:201], v154 offset:16384
	ds_read_b128 v[202:205], v154 offset:17408
	ds_read_b128 v[206:209], v154 offset:18432
	ds_read_b128 v[214:217], v154 offset:19456
	ds_read_b128 v[218:221], v154 offset:20480
	ds_read_b128 v[222:225], v154 offset:21504
	ds_read_b128 v[226:229], v154 offset:22528
	ds_read_b128 v[230:233], v154 offset:23552
	global_load_lds_dwordx4 v[210:211], off
	v_lshl_add_u64 v[234:235], s[28:29], 0, v[136:137]
	s_mov_b32 m0, s40
	s_addc_u32 s57, s29, 0
	global_load_lds_dwordx4 v[234:235], off
	s_mov_b32 m0, s41
	s_nop 0
	global_load_lds_dwordx4 v132, s[56:57]
	s_mov_b32 m0, s42
	s_nop 0
	global_load_lds_dwordx4 v136, s[56:57]
	s_mov_b32 m0, s2
	s_nop 0
	global_load_lds_dwordx4 v130, s[30:31]
	s_mov_b32 m0, s3
	s_nop 0
	global_load_lds_dwordx4 v134, s[30:31]
	s_waitcnt vmcnt(8)
	s_waitcnt lgkmcnt(0)
	s_barrier
	s_waitcnt lgkmcnt(0)
	v_mfma_f32_16x16x32_bf16 v[62:65], v[166:169], v[198:201], v[62:65]
	v_mfma_f32_16x16x32_bf16 v[62:65], v[170:173], v[202:205], v[62:65]
	v_mfma_f32_16x16x32_bf16 v[58:61], v[178:181], v[202:205], v[58:61]
	v_mfma_f32_16x16x32_bf16 v[58:61], v[174:177], v[198:201], v[58:61]
	v_mfma_f32_16x16x32_bf16 v[42:45], v[174:177], v[206:209], v[42:45]
	v_mfma_f32_16x16x32_bf16 v[42:45], v[178:181], v[214:217], v[42:45]
	v_mfma_f32_16x16x32_bf16 v[46:49], v[170:173], v[214:217], v[46:49]
	v_mfma_f32_16x16x32_bf16 v[46:49], v[166:169], v[206:209], v[46:49]
	v_mfma_f32_16x16x32_bf16 v[30:33], v[166:169], v[218:221], v[30:33]
	v_mfma_f32_16x16x32_bf16 v[30:33], v[170:173], v[222:225], v[30:33]
	v_mfma_f32_16x16x32_bf16 v[26:29], v[178:181], v[222:225], v[26:29]
	v_mfma_f32_16x16x32_bf16 v[26:29], v[174:177], v[218:221], v[26:29]
	v_mfma_f32_16x16x32_bf16 v[10:13], v[174:177], v[226:229], v[10:13]
	v_mfma_f32_16x16x32_bf16 v[10:13], v[178:181], v[230:233], v[10:13]
	v_mfma_f32_16x16x32_bf16 v[14:17], v[170:173], v[230:233], v[14:17]
	v_mfma_f32_16x16x32_bf16 v[14:17], v[166:169], v[226:229], v[14:17]
	v_mfma_f32_16x16x32_bf16 v[54:57], v[182:185], v[198:201], v[54:57]
	v_mfma_f32_16x16x32_bf16 v[54:57], v[186:189], v[202:205], v[54:57]
	v_mfma_f32_16x16x32_bf16 v[50:53], v[194:197], v[202:205], v[50:53]
	v_mfma_f32_16x16x32_bf16 v[50:53], v[190:193], v[198:201], v[50:53]
	v_mfma_f32_16x16x32_bf16 v[34:37], v[190:193], v[206:209], v[34:37]
	v_mfma_f32_16x16x32_bf16 v[34:37], v[194:197], v[214:217], v[34:37]
	v_mfma_f32_16x16x32_bf16 v[38:41], v[186:189], v[214:217], v[38:41]
	v_mfma_f32_16x16x32_bf16 v[38:41], v[182:185], v[206:209], v[38:41]
	v_mfma_f32_16x16x32_bf16 v[22:25], v[182:185], v[218:221], v[22:25]
	v_mfma_f32_16x16x32_bf16 v[22:25], v[186:189], v[222:225], v[22:25]
	v_mfma_f32_16x16x32_bf16 v[18:21], v[194:197], v[222:225], v[18:21]
	v_mfma_f32_16x16x32_bf16 v[18:21], v[190:193], v[218:221], v[18:21]
	v_mfma_f32_16x16x32_bf16 v[2:5], v[190:193], v[226:229], v[2:5]
	v_mfma_f32_16x16x32_bf16 v[2:5], v[194:197], v[230:233], v[2:5]
	v_mfma_f32_16x16x32_bf16 v[6:9], v[186:189], v[230:233], v[6:9]
	v_mfma_f32_16x16x32_bf16 v[6:9], v[182:185], v[226:229], v[6:9]
	s_barrier
	ds_read_b128 v[166:169], v156
	ds_read_b128 v[170:173], v156 offset:1024
	ds_read_b128 v[174:177], v156 offset:2048
	ds_read_b128 v[178:181], v156 offset:3072
	ds_read_b128 v[182:185], v157
	ds_read_b128 v[186:189], v157 offset:1024
	ds_read_b128 v[190:193], v157 offset:2048
	ds_read_b128 v[194:197], v157 offset:3072
	s_add_u32 s30, s30, 0x108000
	s_addc_u32 s31, s31, 0
	s_mov_b32 m0, s33
	ds_read_b128 v[198:201], v154 offset:32768
	ds_read_b128 v[202:205], v154 offset:33792
	ds_read_b128 v[206:209], v154 offset:34816
	ds_read_b128 v[214:217], v154 offset:35840
	ds_read_b128 v[218:221], v154 offset:36864
	ds_read_b128 v[222:225], v154 offset:37888
	ds_read_b128 v[226:229], v154 offset:38912
	ds_read_b128 v[230:233], v154 offset:39936
	global_load_lds_dwordx4 v130, s[30:31]
	v_lshl_add_u64 v[236:237], s[30:31], 0, v[134:135]
	s_mov_b32 m0, s34
	s_nop 0
	global_load_lds_dwordx4 v[236:237], off
	s_waitcnt vmcnt(8)
	s_waitcnt lgkmcnt(0)
	s_barrier
	s_waitcnt lgkmcnt(0)
	v_mfma_f32_16x16x32_bf16 v[126:129], v[166:169], v[198:201], v[126:129]
	v_mfma_f32_16x16x32_bf16 v[126:129], v[170:173], v[202:205], v[126:129]
	v_mfma_f32_16x16x32_bf16 v[122:125], v[178:181], v[202:205], v[122:125]
	v_mfma_f32_16x16x32_bf16 v[122:125], v[174:177], v[198:201], v[122:125]
	v_mfma_f32_16x16x32_bf16 v[106:109], v[174:177], v[206:209], v[106:109]
	v_mfma_f32_16x16x32_bf16 v[106:109], v[178:181], v[214:217], v[106:109]
	v_mfma_f32_16x16x32_bf16 v[110:113], v[170:173], v[214:217], v[110:113]
	v_mfma_f32_16x16x32_bf16 v[110:113], v[166:169], v[206:209], v[110:113]
	v_mfma_f32_16x16x32_bf16 v[94:97], v[166:169], v[218:221], v[94:97]
	v_mfma_f32_16x16x32_bf16 v[94:97], v[170:173], v[222:225], v[94:97]
	v_mfma_f32_16x16x32_bf16 v[90:93], v[178:181], v[222:225], v[90:93]
	v_mfma_f32_16x16x32_bf16 v[90:93], v[174:177], v[218:221], v[90:93]
	v_mfma_f32_16x16x32_bf16 v[74:77], v[174:177], v[226:229], v[74:77]
	v_mfma_f32_16x16x32_bf16 v[74:77], v[178:181], v[230:233], v[74:77]
	v_mfma_f32_16x16x32_bf16 v[78:81], v[170:173], v[230:233], v[78:81]
	v_mfma_f32_16x16x32_bf16 v[78:81], v[166:169], v[226:229], v[78:81]
	v_mfma_f32_16x16x32_bf16 v[118:121], v[182:185], v[198:201], v[118:121]
	v_mfma_f32_16x16x32_bf16 v[118:121], v[186:189], v[202:205], v[118:121]
	v_mfma_f32_16x16x32_bf16 v[114:117], v[194:197], v[202:205], v[114:117]
	v_mfma_f32_16x16x32_bf16 v[114:117], v[190:193], v[198:201], v[114:117]
	v_mfma_f32_16x16x32_bf16 v[98:101], v[190:193], v[206:209], v[98:101]
	v_mfma_f32_16x16x32_bf16 v[98:101], v[194:197], v[214:217], v[98:101]
	v_mfma_f32_16x16x32_bf16 v[102:105], v[186:189], v[214:217], v[102:105]
	v_mfma_f32_16x16x32_bf16 v[102:105], v[182:185], v[206:209], v[102:105]
	v_mfma_f32_16x16x32_bf16 v[86:89], v[182:185], v[218:221], v[86:89]
	v_mfma_f32_16x16x32_bf16 v[86:89], v[186:189], v[222:225], v[86:89]
	v_mfma_f32_16x16x32_bf16 v[82:85], v[194:197], v[222:225], v[82:85]
	v_mfma_f32_16x16x32_bf16 v[82:85], v[190:193], v[218:221], v[82:85]
	v_mfma_f32_16x16x32_bf16 v[66:69], v[190:193], v[226:229], v[66:69]
	v_mfma_f32_16x16x32_bf16 v[66:69], v[194:197], v[230:233], v[66:69]
	v_mfma_f32_16x16x32_bf16 v[70:73], v[186:189], v[230:233], v[70:73]
	v_mfma_f32_16x16x32_bf16 v[70:73], v[182:185], v[226:229], v[70:73]
	s_barrier
	s_mov_b32 m0, s43
	v_lshl_add_u64 v[210:211], v[210:211], 0, s[14:15]
	s_add_u32 s28, s28, 0x108080
	ds_read_b128 v[198:201], v154 offset:49152
	ds_read_b128 v[202:205], v154 offset:50176
	ds_read_b128 v[206:209], v154 offset:51200
	ds_read_b128 v[214:217], v154 offset:52224
	ds_read_b128 v[218:221], v154 offset:53248
	ds_read_b128 v[222:225], v154 offset:54272
	ds_read_b128 v[226:229], v154 offset:55296
	ds_read_b128 v[230:233], v154 offset:56320
	global_load_lds_dwordx4 v[210:211], off
	v_lshl_add_u64 v[210:211], v[234:235], 0, s[14:15]
	s_mov_b32 m0, s44
	s_addc_u32 s29, s29, 0
	global_load_lds_dwordx4 v[210:211], off
	s_mov_b32 m0, s45
	s_nop 0
	global_load_lds_dwordx4 v132, s[28:29]
	s_mov_b32 m0, s46
	s_nop 0
	global_load_lds_dwordx4 v136, s[28:29]
	s_mov_b32 m0, s35
	s_nop 0
	global_load_lds_dwordx4 v130, s[26:27]
	s_mov_b32 m0, s36
	s_nop 0
	global_load_lds_dwordx4 v134, s[26:27]
	s_waitcnt vmcnt(8)
	s_waitcnt lgkmcnt(0)
	s_barrier
	s_waitcnt lgkmcnt(0)
	v_mfma_f32_16x16x32_bf16 v[62:65], v[166:169], v[198:201], v[62:65]
	v_mfma_f32_16x16x32_bf16 v[62:65], v[170:173], v[202:205], v[62:65]
	v_mfma_f32_16x16x32_bf16 v[58:61], v[178:181], v[202:205], v[58:61]
	v_mfma_f32_16x16x32_bf16 v[58:61], v[174:177], v[198:201], v[58:61]
	v_mfma_f32_16x16x32_bf16 v[42:45], v[174:177], v[206:209], v[42:45]
	v_mfma_f32_16x16x32_bf16 v[42:45], v[178:181], v[214:217], v[42:45]
	v_mfma_f32_16x16x32_bf16 v[46:49], v[170:173], v[214:217], v[46:49]
	v_mfma_f32_16x16x32_bf16 v[46:49], v[166:169], v[206:209], v[46:49]
	v_mfma_f32_16x16x32_bf16 v[30:33], v[166:169], v[218:221], v[30:33]
	v_mfma_f32_16x16x32_bf16 v[30:33], v[170:173], v[222:225], v[30:33]
	v_mfma_f32_16x16x32_bf16 v[26:29], v[178:181], v[222:225], v[26:29]
	v_mfma_f32_16x16x32_bf16 v[26:29], v[174:177], v[218:221], v[26:29]
	v_mfma_f32_16x16x32_bf16 v[10:13], v[174:177], v[226:229], v[10:13]
	v_mfma_f32_16x16x32_bf16 v[10:13], v[178:181], v[230:233], v[10:13]
	v_mfma_f32_16x16x32_bf16 v[14:17], v[170:173], v[230:233], v[14:17]
	v_mfma_f32_16x16x32_bf16 v[14:17], v[166:169], v[226:229], v[14:17]
	v_mfma_f32_16x16x32_bf16 v[54:57], v[182:185], v[198:201], v[54:57]
	v_mfma_f32_16x16x32_bf16 v[54:57], v[186:189], v[202:205], v[54:57]
	v_mfma_f32_16x16x32_bf16 v[50:53], v[194:197], v[202:205], v[50:53]
	v_mfma_f32_16x16x32_bf16 v[50:53], v[190:193], v[198:201], v[50:53]
	v_mfma_f32_16x16x32_bf16 v[34:37], v[190:193], v[206:209], v[34:37]
	v_mfma_f32_16x16x32_bf16 v[34:37], v[194:197], v[214:217], v[34:37]
	v_mfma_f32_16x16x32_bf16 v[38:41], v[186:189], v[214:217], v[38:41]
	v_mfma_f32_16x16x32_bf16 v[38:41], v[182:185], v[206:209], v[38:41]
	v_mfma_f32_16x16x32_bf16 v[22:25], v[182:185], v[218:221], v[22:25]
	v_mfma_f32_16x16x32_bf16 v[22:25], v[186:189], v[222:225], v[22:25]
	v_mfma_f32_16x16x32_bf16 v[18:21], v[194:197], v[222:225], v[18:21]
	v_mfma_f32_16x16x32_bf16 v[18:21], v[190:193], v[218:221], v[18:21]
	v_mfma_f32_16x16x32_bf16 v[2:5], v[190:193], v[226:229], v[2:5]
	v_mfma_f32_16x16x32_bf16 v[2:5], v[194:197], v[230:233], v[2:5]
	v_mfma_f32_16x16x32_bf16 v[6:9], v[186:189], v[230:233], v[6:9]
	v_mfma_f32_16x16x32_bf16 v[6:9], v[182:185], v[226:229], v[6:9]
	s_barrier
	s_add_i32 s54, s54, 2
	s_add_u32 s22, s22, 0x100
	s_addc_u32 s23, s23, 0
	s_cmp_gt_u32 s54, 61
	s_cbranch_scc0 .LBB0_612
	s_and_b64 vcc, exec, s[16:17]
	s_cbranch_vccz .LBB0_615
	s_barrier

.LBB0_844:
	s_add_i32 s35, s52, 0xfffe8000
	s_and_b32 s34, s30, 0x100
	s_and_b32 s35, s35, 0x3e0000
	s_or_b32 s34, s34, s35
	s_add_u32 s53, s28, s34
	s_addc_u32 s55, s29, 0
	s_add_u32 s34, s30, 0x100
	s_addc_u32 s35, s31, 0
	s_add_i32 s37, s52, 0xffff8000
	s_and_b32 s36, s34, 0x100
	s_and_b32 s37, s37, 0x7e0000
	s_or_b32 s36, s37, s36
	s_add_u32 s36, s28, s36
	s_addc_u32 s37, s29, 0
	s_add_u32 s54, s49, s30
	s_addc_u32 s31, s50, s31
	s_add_i32 s38, s30, 0x180
	s_and_b32 s38, s38, 0x180
	s_and_b32 s39, s52, 0x7e0000
	s_or_b32 s38, s39, s38
	s_add_u32 s56, s28, s38
	s_addc_u32 s57, s29, 0
	s_cmpk_eq_i32 s30, 0x3f00
	s_cselect_b32 s39, s1, s37
	s_cselect_b32 s38, s21, s36
	s_cselect_b32 s37, s23, s31
	s_cselect_b32 s36, s22, s54
	s_cselect_b32 s31, s48, s57
	s_cselect_b32 s30, s27, s56
	s_add_i32 s56, 0, 0x10000
	v_add_u32_e32 v124, s56, v211
	ds_read_b128 v[104:107], v124
	ds_read_b128 v[108:111], v124 offset:1024
	ds_read_b128 v[120:123], v124 offset:2048
	ds_read_b128 v[124:127], v124 offset:3072
	ds_read_b128 v[144:147], v214
	ds_read_b128 v[148:151], v214 offset:1024
	ds_read_b128 v[152:155], v214 offset:2048
	ds_read_b128 v[156:159], v214 offset:3072
	s_add_u32 s54, s53, 0x10080
	s_addc_u32 s55, s55, 0
	s_add_i32 m0, s3, 0xc000
	ds_read_b128 v[160:163], v215
	ds_read_b128 v[164:167], v215 offset:1024
	ds_read_b128 v[168:171], v215 offset:2048
	ds_read_b128 v[172:175], v215 offset:3072
	ds_read_b128 v[176:179], v215 offset:4096
	ds_read_b128 v[180:183], v215 offset:5120
	ds_read_b128 v[192:195], v215 offset:6144
	ds_read_b128 v[196:199], v215 offset:7168
	global_load_lds_dwordx4 v184, s[54:55]
	s_add_i32 m0, s3, 0xe000
	s_nop 0
	global_load_lds_dwordx4 v188, s[54:55]
	s_waitcnt vmcnt(8)
	s_waitcnt lgkmcnt(0)
	s_barrier
	s_waitcnt lgkmcnt(0)
	v_mfma_f32_16x16x32_bf16 v[140:143], v[104:107], v[160:163], v[140:143]
	v_mfma_f32_16x16x32_bf16 v[140:143], v[108:111], v[164:167], v[140:143]
	v_mfma_f32_16x16x32_bf16 v[136:139], v[124:127], v[164:167], v[136:139]
	v_mfma_f32_16x16x32_bf16 v[136:139], v[120:123], v[160:163], v[136:139]
	v_mfma_f32_16x16x32_bf16 v[112:115], v[120:123], v[168:171], v[112:115]
	v_mfma_f32_16x16x32_bf16 v[112:115], v[124:127], v[172:175], v[112:115]
	v_mfma_f32_16x16x32_bf16 v[116:119], v[108:111], v[172:175], v[116:119]
	v_mfma_f32_16x16x32_bf16 v[116:119], v[104:107], v[168:171], v[116:119]
	v_mfma_f32_16x16x32_bf16 v[92:95], v[104:107], v[176:179], v[92:95]
	v_mfma_f32_16x16x32_bf16 v[92:95], v[108:111], v[180:183], v[92:95]
	v_mfma_f32_16x16x32_bf16 v[88:91], v[124:127], v[180:183], v[88:91]
	v_mfma_f32_16x16x32_bf16 v[88:91], v[120:123], v[176:179], v[88:91]
	v_mfma_f32_16x16x32_bf16 v[72:75], v[120:123], v[192:195], v[72:75]
	v_mfma_f32_16x16x32_bf16 v[72:75], v[124:127], v[196:199], v[72:75]
	v_mfma_f32_16x16x32_bf16 v[76:79], v[108:111], v[196:199], v[76:79]
	v_mfma_f32_16x16x32_bf16 v[76:79], v[104:107], v[192:195], v[76:79]
	v_mfma_f32_16x16x32_bf16 v[132:135], v[144:147], v[160:163], v[132:135]
	v_mfma_f32_16x16x32_bf16 v[132:135], v[148:151], v[164:167], v[132:135]
	v_mfma_f32_16x16x32_bf16 v[128:131], v[156:159], v[164:167], v[128:131]
	v_mfma_f32_16x16x32_bf16 v[128:131], v[152:155], v[160:163], v[128:131]
	v_mfma_f32_16x16x32_bf16 v[96:99], v[152:155], v[168:171], v[96:99]
	v_mfma_f32_16x16x32_bf16 v[96:99], v[156:159], v[172:175], v[96:99]
	v_mfma_f32_16x16x32_bf16 v[100:103], v[148:151], v[172:175], v[100:103]
	v_mfma_f32_16x16x32_bf16 v[100:103], v[144:147], v[168:171], v[100:103]
	v_mfma_f32_16x16x32_bf16 v[84:87], v[144:147], v[176:179], v[84:87]
	v_mfma_f32_16x16x32_bf16 v[84:87], v[148:151], v[180:183], v[84:87]
	v_mfma_f32_16x16x32_bf16 v[80:83], v[156:159], v[180:183], v[80:83]
	v_mfma_f32_16x16x32_bf16 v[80:83], v[152:155], v[176:179], v[80:83]
	v_mfma_f32_16x16x32_bf16 v[64:67], v[152:155], v[192:195], v[64:67]
	v_mfma_f32_16x16x32_bf16 v[64:67], v[156:159], v[196:199], v[64:67]
	v_mfma_f32_16x16x32_bf16 v[68:71], v[148:151], v[196:199], v[68:71]
	v_mfma_f32_16x16x32_bf16 v[68:71], v[144:147], v[192:195], v[68:71]
	s_barrier
	s_add_i32 s53, s56, s2
	v_lshl_add_u64 v[200:201], s[36:37], 0, v[186:187]
	s_mov_b32 m0, s53
	ds_read_b128 v[160:163], v215 offset:16384
	ds_read_b128 v[164:167], v215 offset:17408
	ds_read_b128 v[168:171], v215 offset:18432
	ds_read_b128 v[172:175], v215 offset:19456
	ds_read_b128 v[176:179], v215 offset:20480
	ds_read_b128 v[180:183], v215 offset:21504
	ds_read_b128 v[192:195], v215 offset:22528
	ds_read_b128 v[196:199], v215 offset:23552
	global_load_lds_dwordx4 v[200:201], off
	s_add_i32 m0, s53, 0x2000
	s_add_u32 s54, s36, 0x208000
	v_lshl_add_u64 v[202:203], s[36:37], 0, v[190:191]
	s_addc_u32 s55, s37, 0
	s_add_i32 s53, s45, s2
	global_load_lds_dwordx4 v[202:203], off
	s_mov_b32 m0, s53
	s_nop 0
	global_load_lds_dwordx4 v186, s[54:55]
	s_add_i32 m0, s53, 0x2000
	s_nop 0
	global_load_lds_dwordx4 v190, s[54:55]
	s_mov_b32 m0, s3
	s_nop 0
	global_load_lds_dwordx4 v184, s[38:39]
	s_mov_b32 m0, s33
	s_nop 0
	global_load_lds_dwordx4 v188, s[38:39]
	s_waitcnt vmcnt(8)
	s_waitcnt lgkmcnt(0)
	s_barrier
	s_waitcnt lgkmcnt(0)
	v_mfma_f32_16x16x32_bf16 v[60:63], v[104:107], v[160:163], v[60:63]
	v_mfma_f32_16x16x32_bf16 v[60:63], v[108:111], v[164:167], v[60:63]
	v_mfma_f32_16x16x32_bf16 v[56:59], v[124:127], v[164:167], v[56:59]
	v_mfma_f32_16x16x32_bf16 v[56:59], v[120:123], v[160:163], v[56:59]
	v_mfma_f32_16x16x32_bf16 v[40:43], v[120:123], v[168:171], v[40:43]
	v_mfma_f32_16x16x32_bf16 v[40:43], v[124:127], v[172:175], v[40:43]
	v_mfma_f32_16x16x32_bf16 v[44:47], v[108:111], v[172:175], v[44:47]
	v_mfma_f32_16x16x32_bf16 v[44:47], v[104:107], v[168:171], v[44:47]
	v_mfma_f32_16x16x32_bf16 v[28:31], v[104:107], v[176:179], v[28:31]
	v_mfma_f32_16x16x32_bf16 v[28:31], v[108:111], v[180:183], v[28:31]
	v_mfma_f32_16x16x32_bf16 v[24:27], v[124:127], v[180:183], v[24:27]
	v_mfma_f32_16x16x32_bf16 v[24:27], v[120:123], v[176:179], v[24:27]
	v_mfma_f32_16x16x32_bf16 v[8:11], v[120:123], v[192:195], v[8:11]
	v_mfma_f32_16x16x32_bf16 v[8:11], v[124:127], v[196:199], v[8:11]
	v_mfma_f32_16x16x32_bf16 v[12:15], v[108:111], v[196:199], v[12:15]
	v_mfma_f32_16x16x32_bf16 v[12:15], v[104:107], v[192:195], v[12:15]
	v_mfma_f32_16x16x32_bf16 v[52:55], v[144:147], v[160:163], v[52:55]
	v_mfma_f32_16x16x32_bf16 v[52:55], v[148:151], v[164:167], v[52:55]
	v_mfma_f32_16x16x32_bf16 v[48:51], v[156:159], v[164:167], v[48:51]
	v_mfma_f32_16x16x32_bf16 v[48:51], v[152:155], v[160:163], v[48:51]
	v_mfma_f32_16x16x32_bf16 v[32:35], v[152:155], v[168:171], v[32:35]
	v_mfma_f32_16x16x32_bf16 v[32:35], v[156:159], v[172:175], v[32:35]
	v_mfma_f32_16x16x32_bf16 v[36:39], v[148:151], v[172:175], v[36:39]
	v_mfma_f32_16x16x32_bf16 v[36:39], v[144:147], v[168:171], v[36:39]
	v_mfma_f32_16x16x32_bf16 v[20:23], v[144:147], v[176:179], v[20:23]
	v_mfma_f32_16x16x32_bf16 v[20:23], v[148:151], v[180:183], v[20:23]
	v_mfma_f32_16x16x32_bf16 v[16:19], v[156:159], v[180:183], v[16:19]
	v_mfma_f32_16x16x32_bf16 v[16:19], v[152:155], v[176:179], v[16:19]
	v_mfma_f32_16x16x32_bf16 v[0:3], v[152:155], v[192:195], v[0:3]
	v_mfma_f32_16x16x32_bf16 v[0:3], v[156:159], v[196:199], v[0:3]
	v_mfma_f32_16x16x32_bf16 v[4:7], v[148:151], v[196:199], v[4:7]
	v_mfma_f32_16x16x32_bf16 v[4:7], v[144:147], v[192:195], v[4:7]
	s_barrier
	s_add_i32 s53, 0, 0x18000
	s_add_i32 s54, 0, 0x1c000
	v_add_u32_e32 v124, s53, v211
	v_add_u32_e32 v156, s54, v211
	ds_read_b128 v[104:107], v124
	ds_read_b128 v[108:111], v124 offset:1024
	ds_read_b128 v[120:123], v124 offset:2048
	ds_read_b128 v[124:127], v124 offset:3072
	ds_read_b128 v[144:147], v156
	ds_read_b128 v[148:151], v156 offset:1024
	ds_read_b128 v[152:155], v156 offset:2048
	ds_read_b128 v[156:159], v156 offset:3072
	s_add_u32 s38, s38, 0x10000
	s_addc_u32 s39, s39, 0
	s_mov_b32 m0, s40
	ds_read_b128 v[160:163], v215 offset:32768
	ds_read_b128 v[164:167], v215 offset:33792
	ds_read_b128 v[168:171], v215 offset:34816
	ds_read_b128 v[172:175], v215 offset:35840
	ds_read_b128 v[176:179], v215 offset:36864
	ds_read_b128 v[180:183], v215 offset:37888
	ds_read_b128 v[192:195], v215 offset:38912
	ds_read_b128 v[196:199], v215 offset:39936
	global_load_lds_dwordx4 v184, s[38:39]
	v_lshl_add_u64 v[204:205], s[38:39], 0, v[188:189]
	s_mov_b32 m0, s41
	s_nop 0
	global_load_lds_dwordx4 v[204:205], off
	s_waitcnt vmcnt(8)
	s_waitcnt lgkmcnt(0)
	s_barrier
	s_waitcnt lgkmcnt(0)
	v_mfma_f32_16x16x32_bf16 v[140:143], v[104:107], v[160:163], v[140:143]
	v_mfma_f32_16x16x32_bf16 v[140:143], v[108:111], v[164:167], v[140:143]
	v_mfma_f32_16x16x32_bf16 v[136:139], v[124:127], v[164:167], v[136:139]
	v_mfma_f32_16x16x32_bf16 v[136:139], v[120:123], v[160:163], v[136:139]
	v_mfma_f32_16x16x32_bf16 v[112:115], v[120:123], v[168:171], v[112:115]
	v_mfma_f32_16x16x32_bf16 v[112:115], v[124:127], v[172:175], v[112:115]
	v_mfma_f32_16x16x32_bf16 v[116:119], v[108:111], v[172:175], v[116:119]
	v_mfma_f32_16x16x32_bf16 v[116:119], v[104:107], v[168:171], v[116:119]
	v_mfma_f32_16x16x32_bf16 v[92:95], v[104:107], v[176:179], v[92:95]
	v_mfma_f32_16x16x32_bf16 v[92:95], v[108:111], v[180:183], v[92:95]
	v_mfma_f32_16x16x32_bf16 v[88:91], v[124:127], v[180:183], v[88:91]
	v_mfma_f32_16x16x32_bf16 v[88:91], v[120:123], v[176:179], v[88:91]
	v_mfma_f32_16x16x32_bf16 v[72:75], v[120:123], v[192:195], v[72:75]
	v_mfma_f32_16x16x32_bf16 v[72:75], v[124:127], v[196:199], v[72:75]
	v_mfma_f32_16x16x32_bf16 v[76:79], v[108:111], v[196:199], v[76:79]
	v_mfma_f32_16x16x32_bf16 v[76:79], v[104:107], v[192:195], v[76:79]
	v_mfma_f32_16x16x32_bf16 v[132:135], v[144:147], v[160:163], v[132:135]
	v_mfma_f32_16x16x32_bf16 v[132:135], v[148:151], v[164:167], v[132:135]
	v_mfma_f32_16x16x32_bf16 v[128:131], v[156:159], v[164:167], v[128:131]
	v_mfma_f32_16x16x32_bf16 v[128:131], v[152:155], v[160:163], v[128:131]
	v_mfma_f32_16x16x32_bf16 v[96:99], v[152:155], v[168:171], v[96:99]
	v_mfma_f32_16x16x32_bf16 v[96:99], v[156:159], v[172:175], v[96:99]
	v_mfma_f32_16x16x32_bf16 v[100:103], v[148:151], v[172:175], v[100:103]
	v_mfma_f32_16x16x32_bf16 v[100:103], v[144:147], v[168:171], v[100:103]
	v_mfma_f32_16x16x32_bf16 v[84:87], v[144:147], v[176:179], v[84:87]
	v_mfma_f32_16x16x32_bf16 v[84:87], v[148:151], v[180:183], v[84:87]
	v_mfma_f32_16x16x32_bf16 v[80:83], v[156:159], v[180:183], v[80:83]
	v_mfma_f32_16x16x32_bf16 v[80:83], v[152:155], v[176:179], v[80:83]
	v_mfma_f32_16x16x32_bf16 v[64:67], v[152:155], v[192:195], v[64:67]
	v_mfma_f32_16x16x32_bf16 v[64:67], v[156:159], v[196:199], v[64:67]
	v_mfma_f32_16x16x32_bf16 v[68:71], v[148:151], v[196:199], v[68:71]
	v_mfma_f32_16x16x32_bf16 v[68:71], v[144:147], v[192:195], v[68:71]
	s_barrier
	s_add_i32 s38, s53, s2
	v_lshl_add_u64 v[200:201], v[200:201], 0, s[16:17]
	s_mov_b32 m0, s38
	ds_read_b128 v[160:163], v215 offset:49152
	ds_read_b128 v[164:167], v215 offset:50176
	ds_read_b128 v[168:171], v215 offset:51200
	ds_read_b128 v[172:175], v215 offset:52224
	ds_read_b128 v[176:179], v215 offset:53248
	ds_read_b128 v[180:183], v215 offset:54272
	ds_read_b128 v[192:195], v215 offset:55296
	ds_read_b128 v[196:199], v215 offset:56320
	global_load_lds_dwordx4 v[200:201], off
	s_add_i32 m0, s38, 0x2000
	s_add_u32 s36, s36, 0x208080
	v_lshl_add_u64 v[200:201], v[202:203], 0, s[16:17]
	s_addc_u32 s37, s37, 0
	s_add_i32 s38, s54, s2
	global_load_lds_dwordx4 v[200:201], off
	s_mov_b32 m0, s38
	s_nop 0
	global_load_lds_dwordx4 v186, s[36:37]
	s_add_i32 m0, s38, 0x2000
	s_nop 0
	global_load_lds_dwordx4 v190, s[36:37]
	s_mov_b32 m0, s43
	s_nop 0
	global_load_lds_dwordx4 v184, s[30:31]
	v_lshl_add_u64 v[200:201], s[30:31], 0, v[188:189]
	s_mov_b32 m0, s44
	s_nop 0
	global_load_lds_dwordx4 v[200:201], off
	s_waitcnt vmcnt(8)
	s_waitcnt lgkmcnt(0)
	s_barrier
	s_waitcnt lgkmcnt(0)
	v_mfma_f32_16x16x32_bf16 v[60:63], v[104:107], v[160:163], v[60:63]
	v_mfma_f32_16x16x32_bf16 v[60:63], v[108:111], v[164:167], v[60:63]
	v_mfma_f32_16x16x32_bf16 v[56:59], v[124:127], v[164:167], v[56:59]
	v_mfma_f32_16x16x32_bf16 v[56:59], v[120:123], v[160:163], v[56:59]
	v_mfma_f32_16x16x32_bf16 v[40:43], v[120:123], v[168:171], v[40:43]
	v_mfma_f32_16x16x32_bf16 v[40:43], v[124:127], v[172:175], v[40:43]
	v_mfma_f32_16x16x32_bf16 v[44:47], v[108:111], v[172:175], v[44:47]
	v_mfma_f32_16x16x32_bf16 v[44:47], v[104:107], v[168:171], v[44:47]
	v_mfma_f32_16x16x32_bf16 v[28:31], v[104:107], v[176:179], v[28:31]
	v_mfma_f32_16x16x32_bf16 v[28:31], v[108:111], v[180:183], v[28:31]
	v_mfma_f32_16x16x32_bf16 v[24:27], v[124:127], v[180:183], v[24:27]
	v_mfma_f32_16x16x32_bf16 v[24:27], v[120:123], v[176:179], v[24:27]
	v_mfma_f32_16x16x32_bf16 v[8:11], v[120:123], v[192:195], v[8:11]
	v_mfma_f32_16x16x32_bf16 v[8:11], v[124:127], v[196:199], v[8:11]
	v_mfma_f32_16x16x32_bf16 v[12:15], v[108:111], v[196:199], v[12:15]
	v_mfma_f32_16x16x32_bf16 v[12:15], v[104:107], v[192:195], v[12:15]
	v_mfma_f32_16x16x32_bf16 v[52:55], v[144:147], v[160:163], v[52:55]
	v_mfma_f32_16x16x32_bf16 v[52:55], v[148:151], v[164:167], v[52:55]
	v_mfma_f32_16x16x32_bf16 v[48:51], v[156:159], v[164:167], v[48:51]
	v_mfma_f32_16x16x32_bf16 v[48:51], v[152:155], v[160:163], v[48:51]
	v_mfma_f32_16x16x32_bf16 v[32:35], v[152:155], v[168:171], v[32:35]
	v_mfma_f32_16x16x32_bf16 v[32:35], v[156:159], v[172:175], v[32:35]
	v_mfma_f32_16x16x32_bf16 v[36:39], v[148:151], v[172:175], v[36:39]
	v_mfma_f32_16x16x32_bf16 v[36:39], v[144:147], v[168:171], v[36:39]
	v_mfma_f32_16x16x32_bf16 v[20:23], v[144:147], v[176:179], v[20:23]
	v_mfma_f32_16x16x32_bf16 v[20:23], v[148:151], v[180:183], v[20:23]
	v_mfma_f32_16x16x32_bf16 v[16:19], v[156:159], v[180:183], v[16:19]
	v_mfma_f32_16x16x32_bf16 v[16:19], v[152:155], v[176:179], v[16:19]
	v_mfma_f32_16x16x32_bf16 v[0:3], v[152:155], v[192:195], v[0:3]
	v_mfma_f32_16x16x32_bf16 v[0:3], v[156:159], v[196:199], v[0:3]
	v_mfma_f32_16x16x32_bf16 v[4:7], v[148:151], v[196:199], v[4:7]
	v_mfma_f32_16x16x32_bf16 v[4:7], v[144:147], v[192:195], v[4:7]
	s_barrier
	s_add_i32 s51, s51, 2
	s_add_i32 s52, s52, 0x10000
	s_cmpk_gt_u32 s51, 0x7d
	s_mov_b64 s[30:31], s[34:35]
	s_cbranch_scc0 .LBB0_844
	s_and_b64 vcc, exec, s[18:19]
	s_cbranch_vccz .LBB0_847
	s_barrier
